# rwkv2 role-3 output segment: Vf/bonus LDS reads hoisted to the segment head (on top of F4 epilogue prefetch and W2/A2 slice load unroll)
# speedup vs baseline: 1.0628x; 1.0208x over previous
; __device__ __forceinline__ u16 f2bf(float f) { return (u16)(pk2(f, 0.f) & 0xffffu); }
; __device__ unsigned long long rwkv2_phase(const Params& p, unsigned char* smem) {
;     ...
;         for (int e = tid; e < 6144; e += 512) { const int j = e >> 6, k = e & 63; W2t[k * 104 + j] = f2bf(p.in[30][(size_t)j * 4096 + hc + k]); A2t[k * 104 + j] = f2bf(p.in[33][(size_t)j * 4096 + hc + k]); }
.LBB0_847:
	s_movk_i32 s28, 0x15ff
	global_load_dword v180, v[4:5], off
	global_load_dword v181, v[42:43], off
	v_lshl_add_u64 v[4:5], v[4:5], 0, s[84:85]
	v_lshl_add_u64 v[42:43], v[42:43], 0, s[84:85]
	global_load_dword v182, v[4:5], off
	global_load_dword v183, v[42:43], off
	v_lshl_add_u64 v[4:5], v[4:5], 0, s[84:85]
	v_lshl_add_u64 v[42:43], v[42:43], 0, s[84:85]
	global_load_dword v184, v[4:5], off
	global_load_dword v185, v[42:43], off
	v_lshl_add_u64 v[4:5], v[4:5], 0, s[84:85]
	v_lshl_add_u64 v[42:43], v[42:43], 0, s[84:85]
	global_load_dword v186, v[4:5], off
	global_load_dword v187, v[42:43], off
	v_lshl_add_u64 v[4:5], v[4:5], 0, s[84:85]
	v_lshl_add_u64 v[42:43], v[42:43], 0, s[84:85]
	global_load_dword v188, v[4:5], off
	global_load_dword v189, v[42:43], off
	v_lshl_add_u64 v[4:5], v[4:5], 0, s[84:85]
	v_lshl_add_u64 v[42:43], v[42:43], 0, s[84:85]
	global_load_dword v190, v[4:5], off
	global_load_dword v191, v[42:43], off
	v_lshl_add_u64 v[4:5], v[4:5], 0, s[84:85]
	v_lshl_add_u64 v[42:43], v[42:43], 0, s[84:85]
	global_load_dword v192, v[4:5], off
	global_load_dword v193, v[42:43], off
	v_lshl_add_u64 v[4:5], v[4:5], 0, s[84:85]
	v_lshl_add_u64 v[42:43], v[42:43], 0, s[84:85]
	global_load_dword v194, v[4:5], off
	global_load_dword v195, v[42:43], off
	v_lshl_add_u64 v[4:5], v[4:5], 0, s[84:85]
	v_lshl_add_u64 v[42:43], v[42:43], 0, s[84:85]
	global_load_dword v196, v[4:5], off
	global_load_dword v197, v[42:43], off
	v_lshl_add_u64 v[4:5], v[4:5], 0, s[84:85]
	v_lshl_add_u64 v[42:43], v[42:43], 0, s[84:85]
	global_load_dword v198, v[4:5], off
	global_load_dword v199, v[42:43], off
	v_lshl_add_u64 v[4:5], v[4:5], 0, s[84:85]
	v_lshl_add_u64 v[42:43], v[42:43], 0, s[84:85]
	global_load_dword v200, v[4:5], off
	global_load_dword v201, v[42:43], off
	v_lshl_add_u64 v[4:5], v[4:5], 0, s[84:85]
	v_lshl_add_u64 v[42:43], v[42:43], 0, s[84:85]
	global_load_dword v202, v[4:5], off
	global_load_dword v46, v[42:43], off
	v_lshl_add_u64 v[4:5], v[4:5], 0, s[84:85]
	v_lshl_add_u64 v[42:43], v[42:43], 0, s[84:85]
	v_add_u32_e32 v44, 0x1800, v44
	s_waitcnt vmcnt(23)
	v_cvt_pk_bf16_f32 v180, v180, v2
	ds_write_b16 v3, v180
	s_waitcnt vmcnt(22)
	v_cvt_pk_bf16_f32 v181, v181, v2
	ds_write_b16 v3, v181 offset:13312
	s_waitcnt vmcnt(21)
	v_cvt_pk_bf16_f32 v182, v182, v2
	ds_write_b16 v3, v182 offset:16
	s_waitcnt vmcnt(20)
	v_cvt_pk_bf16_f32 v183, v183, v2
	ds_write_b16 v3, v183 offset:13328
	s_waitcnt vmcnt(19)
	v_cvt_pk_bf16_f32 v184, v184, v2
	ds_write_b16 v3, v184 offset:32
	s_waitcnt vmcnt(18)
	v_cvt_pk_bf16_f32 v185, v185, v2
	ds_write_b16 v3, v185 offset:13344
	s_waitcnt vmcnt(17)
	v_cvt_pk_bf16_f32 v186, v186, v2
	ds_write_b16 v3, v186 offset:48
	s_waitcnt vmcnt(16)
	v_cvt_pk_bf16_f32 v187, v187, v2
	ds_write_b16 v3, v187 offset:13360
	s_waitcnt vmcnt(15)
	v_cvt_pk_bf16_f32 v188, v188, v2
	ds_write_b16 v3, v188 offset:64
	s_waitcnt vmcnt(14)
	v_cvt_pk_bf16_f32 v189, v189, v2
	ds_write_b16 v3, v189 offset:13376
	s_waitcnt vmcnt(13)
	v_cvt_pk_bf16_f32 v190, v190, v2
	ds_write_b16 v3, v190 offset:80
	s_waitcnt vmcnt(12)
	v_cvt_pk_bf16_f32 v191, v191, v2
	ds_write_b16 v3, v191 offset:13392
	s_waitcnt vmcnt(11)
	v_cvt_pk_bf16_f32 v192, v192, v2
	ds_write_b16 v3, v192 offset:96
	s_waitcnt vmcnt(10)
	v_cvt_pk_bf16_f32 v193, v193, v2
	ds_write_b16 v3, v193 offset:13408
	s_waitcnt vmcnt(9)
	v_cvt_pk_bf16_f32 v194, v194, v2
	ds_write_b16 v3, v194 offset:112
	s_waitcnt vmcnt(8)
	v_cvt_pk_bf16_f32 v195, v195, v2
	ds_write_b16 v3, v195 offset:13424
	s_waitcnt vmcnt(7)
	v_cvt_pk_bf16_f32 v196, v196, v2
	ds_write_b16 v3, v196 offset:128
	s_waitcnt vmcnt(6)
	v_cvt_pk_bf16_f32 v197, v197, v2
	ds_write_b16 v3, v197 offset:13440
	s_waitcnt vmcnt(5)
	v_cvt_pk_bf16_f32 v198, v198, v2
	ds_write_b16 v3, v198 offset:144
	s_waitcnt vmcnt(4)
	v_cvt_pk_bf16_f32 v199, v199, v2
	ds_write_b16 v3, v199 offset:13456
	s_waitcnt vmcnt(3)
	v_cvt_pk_bf16_f32 v200, v200, v2
	ds_write_b16 v3, v200 offset:160
	s_waitcnt vmcnt(2)
	v_cvt_pk_bf16_f32 v201, v201, v2
	ds_write_b16 v3, v201 offset:13472
	s_waitcnt vmcnt(1)
	v_cvt_pk_bf16_f32 v202, v202, v2
	ds_write_b16 v3, v202 offset:176
	s_waitcnt vmcnt(0)
	v_cvt_pk_bf16_f32 v45, v46, v2
	ds_write_b16 v3, v45 offset:13488
	v_add_u32_e32 v3, 0xc0, v3
	s_or_b64 exec, exec, s[26:27]
	s_mov_b32 s33, 0
	s_mov_b64 s[68:69], 0
	v_mov_b32_e32 v3, v156
	s_branch .LBB0_850

; __device__ __forceinline__ u16 f2bf(float f) { return (u16)(pk2(f, 0.f) & 0xffffu); }
; __device__ __forceinline__ float row16_sum(float v) { v += dppf<0xB1>(v); v += dppf<0x4E>(v); v += dppf<0x141>(v); v += dppf<0x140>(v); return v; }
; __device__ unsigned long long rwkv2_phase(const Params& p, unsigned char* smem) {
;     ...
;                 if (doY) {
; #pragma unroll
;                     for (int r = 0; r < 4; ++r) { const int t = 4 * lq + r; const size_t row = (size_t)(b * SEQL + cs * TC + t);
;                         const float mu = row16_sum(accY[0][r] + accY[1][r] + accY[2][r] + accY[3][r]) * (1.0f / 64.0f);
;                         float d[4], s2 = 0.f;
; #pragma unroll
;                         for (int nt = 0; nt < 4; ++nt) { d[nt] = accY[nt][r] - mu; s2 += d[nt] * d[nt]; }
;                         const float rs = rsqrtf(row16_sum(s2) * (1.0f / 64.0f) + 64e-5f), bon = bonus[t];
; #pragma unroll
;                         for (int nt = 0; nt < 4; ++nt) R[row * 4096 + hc + 16 * nt + l15] = f2bf(d[nt] * rs * gng[nt] + gnb[nt] + bon * Vf[t * 64 + 16 * nt + l15]); }
.LBB0_875:
	s_waitcnt lgkmcnt(0)
	s_barrier
	s_and_b64 s[28:29], s[28:29], s[30:31]
	s_andn2_b64 vcc, exec, s[28:29]
	s_cbranch_vccnz .LBB0_869
	v_lshl_add_u32 v187, v3, 4, s56
	v_lshlrev_b32_e32 v188, 10, v3
	v_lshlrev_b32_e32 v189, 2, v5
	v_add3_u32 v188, s71, v189, v188
	ds_read_b32 v190, v187 offset:10496
	ds_read_b32 v191, v187 offset:10500
	ds_read_b32 v192, v187 offset:10504
	ds_read_b32 v193, v187 offset:10508
	ds_read_b32 v194, v188 offset:58240
	ds_read_b32 v195, v188 offset:58304
	ds_read_b32 v196, v188 offset:58368
	ds_read_b32 v197, v188 offset:58432
	ds_read_b32 v198, v188 offset:58496
	ds_read_b32 v199, v188 offset:58560
	ds_read_b32 v200, v188 offset:58624
	ds_read_b32 v201, v188 offset:58688
	ds_read_b32 v202, v188 offset:58752
	ds_read_b32 v203, v188 offset:58816
	ds_read_b32 v204, v188 offset:58880
	ds_read_b32 v205, v188 offset:58944
	ds_read_b32 v206, v188 offset:59008
	ds_read_b32 v207, v188 offset:59072
	ds_read_b32 v208, v188 offset:59136
	ds_read_b32 v209, v188 offset:59200
	v_add_f32_e32 v99, v66, v50
	v_add_f32_e32 v99, v90, v99
	v_add_f32_e32 v99, v94, v99
	v_mov_b32_e32 v180, v50
	v_mov_b32_e32 v181, v66
	v_add_f32_dpp v99, v99, v99 quad_perm:[1,0,3,2] row_mask:0xf bank_mask:0xf bound_ctrl:1
	v_mov_b32_e32 v184, v94
	v_mov_b32_e32 v185, v90
	v_add_f32_dpp v99, v99, v99 quad_perm:[2,3,0,1] row_mask:0xf bank_mask:0xf bound_ctrl:1
	s_add_i32 s28, s68, s69
	v_lshlrev_b32_e32 v186, 2, v5
	v_add_f32_dpp v99, v99, v99 row_half_mirror row_mask:0xf bank_mask:0xf bound_ctrl:1
	v_lshl_add_u32 v98, v3, 2, s28
	v_subrev_u32_e32 v100, 32, v98
	v_add_f32_dpp v99, v99, v99 row_mirror row_mask:0xf bank_mask:0xf bound_ctrl:1
	v_mul_f32_e32 v178, 0x3c800000, v99
	v_pk_add_f32 v[180:181], v[180:181], v[178:179] op_sel_hi:[1,0] neg_lo:[0,1] neg_hi:[0,1]
	v_pk_add_f32 v[178:179], v[184:185], v[178:179] op_sel_hi:[1,0] neg_lo:[0,1] neg_hi:[0,1]
	v_pk_mul_f32 v[182:183], v[180:181], v[180:181]
	v_pk_mul_f32 v[184:185], v[178:179], v[178:179]
	v_add_f32_e32 v99, v182, v183
	v_add_f32_e32 v99, v185, v99
	v_add_f32_e32 v99, v184, v99
	v_lshlrev_b32_e32 v4, 1, v5
	v_mov_b32_e32 v5, v2
	v_add_f32_dpp v99, v99, v99 quad_perm:[1,0,3,2] row_mask:0xf bank_mask:0xf bound_ctrl:1
	v_ashrrev_i32_e32 v101, 31, v100
	v_lshl_add_u64 v[4:5], s[26:27], 0, v[4:5]
	v_add_f32_dpp v99, v99, v99 quad_perm:[2,3,0,1] row_mask:0xf bank_mask:0xf bound_ctrl:1
	v_lshlrev_b64 v[100:101], 13, v[100:101]
	v_lshl_add_u64 v[100:101], v[4:5], 0, v[100:101]
	v_add_f32_dpp v99, v99, v99 row_half_mirror row_mask:0xf bank_mask:0xf bound_ctrl:1
	v_mov_b32_e32 v185, v91
	s_nop 0
	v_add_f32_dpp v99, v99, v99 row_mirror row_mask:0xf bank_mask:0xf bound_ctrl:1
	v_fmamk_f32 v99, v99, 0x3c800000, v163
	v_cmp_gt_f32_e32 vcc, s35, v99
	v_mul_f32_e32 v182, 0x4b800000, v99
	s_nop 0
	v_cndmask_b32_e32 v99, v99, v182, vcc
	v_rsq_f32_e32 v99, v99
	s_nop 0
	v_mul_f32_e32 v182, 0x45800000, v99
	v_cndmask_b32_e32 v182, v99, v182, vcc
	v_lshl_add_u32 v99, v3, 4, s56
	v_lshlrev_b32_e32 v3, 10, v3
	v_add3_u32 v3, s71, v186, v3
	s_waitcnt lgkmcnt(0)
	v_mov_b32_e32 v183, v190
	v_mov_b32_e32 v184, v194
	v_mul_f32_e32 v180, v180, v182
	v_fma_f32 v180, v170, v180, v171
	v_mul_f32_e32 v179, v179, v182
	v_fma_f32 v179, v174, v179, v175
	s_waitcnt lgkmcnt(0)
	v_fmac_f32_e32 v180, v183, v184
	v_cvt_pk_bf16_f32 v180, v180, v2
	global_store_short v[100:101], v180, off
	v_mul_f32_e32 v180, v181, v182
	v_mov_b32_e32 v181, v195
	v_fma_f32 v180, v172, v180, v173
	v_mul_f32_e32 v178, v178, v182
	v_fma_f32 v178, v176, v178, v177
	v_mov_b32_e32 v184, v95
	s_waitcnt lgkmcnt(0)
	v_fmac_f32_e32 v180, v183, v181
	v_cvt_pk_bf16_f32 v180, v180, v2
	global_store_short v[100:101], v180, off offset:32
	v_mov_b32_e32 v180, v196
	v_mov_b32_e32 v181, v67
	s_waitcnt lgkmcnt(0)
	v_fmac_f32_e32 v179, v183, v180
	v_cvt_pk_bf16_f32 v179, v179, v2
	global_store_short v[100:101], v179, off offset:64
	v_mov_b32_e32 v179, v197
	v_mov_b32_e32 v180, v51
	s_waitcnt lgkmcnt(0)
	v_fmac_f32_e32 v178, v183, v179
	v_cvt_pk_bf16_f32 v178, v178, v2
	global_store_short v[100:101], v178, off offset:96
	v_add_f32_e32 v101, v67, v51
	v_add_f32_e32 v101, v91, v101
	v_add_f32_e32 v101, v95, v101
	v_subrev_u32_e32 v100, 31, v98
	s_nop 0
	v_add_f32_dpp v101, v101, v101 quad_perm:[1,0,3,2] row_mask:0xf bank_mask:0xf bound_ctrl:1
	s_nop 1
	v_add_f32_dpp v101, v101, v101 quad_perm:[2,3,0,1] row_mask:0xf bank_mask:0xf bound_ctrl:1
	s_nop 1
	v_add_f32_dpp v101, v101, v101 row_half_mirror row_mask:0xf bank_mask:0xf bound_ctrl:1
	s_nop 1
	v_add_f32_dpp v101, v101, v101 row_mirror row_mask:0xf bank_mask:0xf bound_ctrl:1
	v_mul_f32_e32 v178, 0x3c800000, v101
	v_pk_add_f32 v[180:181], v[180:181], v[178:179] op_sel_hi:[1,0] neg_lo:[0,1] neg_hi:[0,1]
	v_pk_add_f32 v[178:179], v[184:185], v[178:179] op_sel_hi:[1,0] neg_lo:[0,1] neg_hi:[0,1]
	v_pk_mul_f32 v[182:183], v[180:181], v[180:181]
	v_pk_mul_f32 v[184:185], v[178:179], v[178:179]
	v_add_f32_e32 v101, v182, v183
	v_add_f32_e32 v101, v185, v101
	v_add_f32_e32 v182, v184, v101
	v_mov_b32_e32 v184, v198
	v_ashrrev_i32_e32 v101, 31, v100
	v_add_f32_dpp v182, v182, v182 quad_perm:[1,0,3,2] row_mask:0xf bank_mask:0xf bound_ctrl:1
	v_lshlrev_b64 v[100:101], 13, v[100:101]
	v_lshl_add_u64 v[100:101], v[4:5], 0, v[100:101]
	v_add_f32_dpp v182, v182, v182 quad_perm:[2,3,0,1] row_mask:0xf bank_mask:0xf bound_ctrl:1
	v_mov_b32_e32 v185, v92
	s_nop 0
	v_add_f32_dpp v182, v182, v182 row_half_mirror row_mask:0xf bank_mask:0xf bound_ctrl:1
	s_nop 1
	v_add_f32_dpp v182, v182, v182 row_mirror row_mask:0xf bank_mask:0xf bound_ctrl:1
	v_fmamk_f32 v182, v182, 0x3c800000, v163
	v_cmp_gt_f32_e32 vcc, s35, v182
	v_mul_f32_e32 v183, 0x4b800000, v182
	s_nop 0
	v_cndmask_b32_e32 v182, v182, v183, vcc
	v_rsq_f32_e32 v182, v182
	s_nop 0
	v_mul_f32_e32 v183, 0x45800000, v182
	v_cndmask_b32_e32 v182, v182, v183, vcc
	v_mov_b32_e32 v183, v191
	v_mul_f32_e32 v180, v180, v182
	v_fma_f32 v180, v170, v180, v171
	v_mul_f32_e32 v179, v179, v182
	v_fma_f32 v179, v174, v179, v175
	s_waitcnt lgkmcnt(0)
; __device__ __forceinline__ u16 f2bf(float f) { return (u16)(pk2(f, 0.f) & 0xffffu); }
; __device__ __forceinline__ float row16_sum(float v) { v += dppf<0xB1>(v); v += dppf<0x4E>(v); v += dppf<0x141>(v); v += dppf<0x140>(v); return v; }
; __device__ unsigned long long rwkv2_phase(const Params& p, unsigned char* smem) {
;     ...
;                 if (doY) {
; #pragma unroll
;                     for (int r = 0; r < 4; ++r) { const int t = 4 * lq + r; const size_t row = (size_t)(b * SEQL + cs * TC + t);
;                         const float mu = row16_sum(accY[0][r] + accY[1][r] + accY[2][r] + accY[3][r]) * (1.0f / 64.0f);
;                         float d[4], s2 = 0.f;
; #pragma unroll
;                         for (int nt = 0; nt < 4; ++nt) { d[nt] = accY[nt][r] - mu; s2 += d[nt] * d[nt]; }
;                         const float rs = rsqrtf(row16_sum(s2) * (1.0f / 64.0f) + 64e-5f), bon = bonus[t];
; #pragma unroll
;                         for (int nt = 0; nt < 4; ++nt) R[row * 4096 + hc + 16 * nt + l15] = f2bf(d[nt] * rs * gng[nt] + gnb[nt] + bon * Vf[t * 64 + 16 * nt + l15]); }
	v_fmac_f32_e32 v180, v183, v184
	v_cvt_pk_bf16_f32 v180, v180, v2
	global_store_short v[100:101], v180, off
	v_mul_f32_e32 v180, v181, v182
	v_mov_b32_e32 v181, v199
	v_fma_f32 v180, v172, v180, v173
	v_mul_f32_e32 v178, v178, v182
	v_fma_f32 v178, v176, v178, v177
	v_mov_b32_e32 v184, v96
	s_waitcnt lgkmcnt(0)
	v_fmac_f32_e32 v180, v183, v181
	v_cvt_pk_bf16_f32 v180, v180, v2
	global_store_short v[100:101], v180, off offset:32
	v_mov_b32_e32 v180, v200
	v_mov_b32_e32 v181, v68
	s_waitcnt lgkmcnt(0)
	v_fmac_f32_e32 v179, v183, v180
	v_cvt_pk_bf16_f32 v179, v179, v2
	global_store_short v[100:101], v179, off offset:64
	v_mov_b32_e32 v179, v201
	v_mov_b32_e32 v180, v52
	s_waitcnt lgkmcnt(0)
	v_fmac_f32_e32 v178, v183, v179
	v_cvt_pk_bf16_f32 v178, v178, v2
	global_store_short v[100:101], v178, off offset:96
	v_add_f32_e32 v101, v68, v52
	v_add_f32_e32 v101, v92, v101
	v_add_f32_e32 v101, v96, v101
	v_subrev_u32_e32 v100, 30, v98
	s_nop 0
	v_add_f32_dpp v101, v101, v101 quad_perm:[1,0,3,2] row_mask:0xf bank_mask:0xf bound_ctrl:1
	s_nop 1
	v_add_f32_dpp v101, v101, v101 quad_perm:[2,3,0,1] row_mask:0xf bank_mask:0xf bound_ctrl:1
	s_nop 1
	v_add_f32_dpp v101, v101, v101 row_half_mirror row_mask:0xf bank_mask:0xf bound_ctrl:1
	s_nop 1
	v_add_f32_dpp v101, v101, v101 row_mirror row_mask:0xf bank_mask:0xf bound_ctrl:1
	v_mul_f32_e32 v178, 0x3c800000, v101
	v_pk_add_f32 v[180:181], v[180:181], v[178:179] op_sel_hi:[1,0] neg_lo:[0,1] neg_hi:[0,1]
	v_pk_add_f32 v[178:179], v[184:185], v[178:179] op_sel_hi:[1,0] neg_lo:[0,1] neg_hi:[0,1]
	v_pk_mul_f32 v[182:183], v[180:181], v[180:181]
	v_pk_mul_f32 v[184:185], v[178:179], v[178:179]
	v_add_f32_e32 v101, v182, v183
	v_add_f32_e32 v101, v185, v101
	v_add_f32_e32 v182, v184, v101
	v_mov_b32_e32 v184, v202
	v_ashrrev_i32_e32 v101, 31, v100
	v_add_f32_dpp v182, v182, v182 quad_perm:[1,0,3,2] row_mask:0xf bank_mask:0xf bound_ctrl:1
	v_lshlrev_b64 v[100:101], 13, v[100:101]
	v_lshl_add_u64 v[100:101], v[4:5], 0, v[100:101]
	v_add_f32_dpp v182, v182, v182 quad_perm:[2,3,0,1] row_mask:0xf bank_mask:0xf bound_ctrl:1
	s_nop 1
	v_add_f32_dpp v182, v182, v182 row_half_mirror row_mask:0xf bank_mask:0xf bound_ctrl:1
	s_nop 1
	v_add_f32_dpp v182, v182, v182 row_mirror row_mask:0xf bank_mask:0xf bound_ctrl:1
	v_fmamk_f32 v182, v182, 0x3c800000, v163
	v_cmp_gt_f32_e32 vcc, s35, v182
	v_mul_f32_e32 v183, 0x4b800000, v182
	s_nop 0
	v_cndmask_b32_e32 v182, v182, v183, vcc
	v_rsq_f32_e32 v182, v182
	s_nop 0
	v_mul_f32_e32 v183, 0x45800000, v182
	v_cndmask_b32_e32 v182, v182, v183, vcc
	v_mov_b32_e32 v183, v192
	v_mul_f32_e32 v180, v180, v182
	v_fma_f32 v180, v170, v180, v171
	v_mul_f32_e32 v179, v179, v182
	v_fma_f32 v179, v174, v179, v175
	s_waitcnt lgkmcnt(0)
	v_fmac_f32_e32 v180, v183, v184
	v_cvt_pk_bf16_f32 v180, v180, v2
	global_store_short v[100:101], v180, off
	v_mul_f32_e32 v180, v181, v182
	v_mov_b32_e32 v181, v203
	v_fma_f32 v180, v172, v180, v173
	v_mul_f32_e32 v178, v178, v182
	v_fma_f32 v178, v176, v178, v177
	v_mov_b32_e32 v182, v97
	s_waitcnt lgkmcnt(0)
	v_fmac_f32_e32 v180, v183, v181
	v_cvt_pk_bf16_f32 v180, v180, v2
	global_store_short v[100:101], v180, off offset:32
	v_mov_b32_e32 v180, v204
	s_waitcnt lgkmcnt(0)
	v_fmac_f32_e32 v179, v183, v180
	v_cvt_pk_bf16_f32 v179, v179, v2
	global_store_short v[100:101], v179, off offset:64
	v_mov_b32_e32 v179, v205
	s_waitcnt lgkmcnt(0)
	v_fmac_f32_e32 v178, v183, v179
	v_cvt_pk_bf16_f32 v178, v178, v2
	global_store_short v[100:101], v178, off offset:96
	v_subrev_u32_e32 v100, 29, v98
	v_add_f32_e32 v98, v69, v53
	v_add_f32_e32 v98, v93, v98
	v_add_f32_e32 v98, v97, v98
	v_mov_b32_e32 v178, v53
	v_mov_b32_e32 v179, v69
	v_add_f32_dpp v98, v98, v98 quad_perm:[1,0,3,2] row_mask:0xf bank_mask:0xf bound_ctrl:1
	v_mov_b32_e32 v183, v93
	v_ashrrev_i32_e32 v101, 31, v100
	v_add_f32_dpp v98, v98, v98 quad_perm:[2,3,0,1] row_mask:0xf bank_mask:0xf bound_ctrl:1
	s_nop 1
	v_add_f32_dpp v98, v98, v98 row_half_mirror row_mask:0xf bank_mask:0xf bound_ctrl:1
	s_nop 1
	v_add_f32_dpp v98, v98, v98 row_mirror row_mask:0xf bank_mask:0xf bound_ctrl:1
	v_mul_f32_e32 v98, 0x3c800000, v98
	v_pk_add_f32 v[178:179], v[178:179], v[98:99] op_sel_hi:[1,0] neg_lo:[0,1] neg_hi:[0,1]
	v_pk_add_f32 v[182:183], v[182:183], v[98:99] op_sel_hi:[1,0] neg_lo:[0,1] neg_hi:[0,1]
	v_pk_mul_f32 v[180:181], v[178:179], v[178:179]
	v_pk_mul_f32 v[184:185], v[182:183], v[182:183]
	v_add_f32_e32 v98, v180, v181
	v_add_f32_e32 v98, v185, v98
	v_add_f32_e32 v98, v184, v98
	v_mov_b32_e32 v181, v193
	s_nop 0
	v_add_f32_dpp v98, v98, v98 quad_perm:[1,0,3,2] row_mask:0xf bank_mask:0xf bound_ctrl:1
	s_nop 1
	v_add_f32_dpp v98, v98, v98 quad_perm:[2,3,0,1] row_mask:0xf bank_mask:0xf bound_ctrl:1
	s_nop 1
	v_add_f32_dpp v98, v98, v98 row_half_mirror row_mask:0xf bank_mask:0xf bound_ctrl:1
	s_nop 1
	v_add_f32_dpp v98, v98, v98 row_mirror row_mask:0xf bank_mask:0xf bound_ctrl:1
	v_fmamk_f32 v98, v98, 0x3c800000, v163
	v_cmp_gt_f32_e32 vcc, s35, v98
	v_mul_f32_e32 v180, 0x4b800000, v98
	s_nop 0
	v_cndmask_b32_e32 v98, v98, v180, vcc
	v_rsq_f32_e32 v98, v98
	s_nop 0
	v_mul_f32_e32 v180, 0x45800000, v98
	v_cndmask_b32_e32 v180, v98, v180, vcc
	v_lshlrev_b64 v[98:99], 13, v[100:101]
	v_lshl_add_u64 v[4:5], v[4:5], 0, v[98:99]
	v_mov_b32_e32 v99, v206
	v_mul_f32_e32 v98, v178, v180
	v_fma_f32 v98, v170, v98, v171
	s_waitcnt lgkmcnt(0)
	v_fmac_f32_e32 v98, v181, v99
	v_cvt_pk_bf16_f32 v98, v98, v2
	v_mov_b32_e32 v99, v207
	global_store_short v[4:5], v98, off
	v_mul_f32_e32 v98, v179, v180
	v_fma_f32 v98, v172, v98, v173
	s_waitcnt lgkmcnt(0)
	v_fmac_f32_e32 v98, v181, v99
	v_cvt_pk_bf16_f32 v98, v98, v2
	v_mov_b32_e32 v99, v208
	global_store_short v[4:5], v98, off offset:32
	v_mul_f32_e32 v98, v183, v180
	v_fma_f32 v98, v174, v98, v175
	s_waitcnt lgkmcnt(0)
	v_fmac_f32_e32 v98, v181, v99
	v_cvt_pk_bf16_f32 v98, v98, v2
	v_mov_b32_e32 v3, v209
	global_store_short v[4:5], v98, off offset:64
	v_mul_f32_e32 v98, v182, v180
	v_fma_f32 v98, v176, v98, v177
	s_waitcnt lgkmcnt(0)
	v_fmac_f32_e32 v98, v181, v3
	v_cvt_pk_bf16_f32 v3, v98, v2
	global_store_short v[4:5], v3, off offset:96
	s_branch .LBB0_869

; #define PG8_STAGE(bufoff, gbase, voff) do { _Pragma("unroll") for (int _i = 0; _i < 2; ++_i) \
;         __builtin_amdgcn_global_load_lds((const unsigned*)((const char*)(gbase) + (voff)[_i]), (PG8_LAS unsigned*)(lds + (bufoff) + ldsw + _i * 8192), 16, 0, 0); } while (0)
; #define PG8_LDA(dst, b, h) do { _Pragma("unroll") for (int m = 0; m < 4; ++m) _Pragma("unroll") for (int k = 0; k < 2; ++k) dst[m][k] = *(const PG8_LAS bf16x8*)(lds + PG8_SA(b, h) + aoff + m * 2048 + k * 1024); } while (0)
; #define PG8_LDB(dst, b, h) do { _Pragma("unroll") for (int n = 0; n < 2; ++n) _Pragma("unroll") for (int k = 0; k < 2; ++k) dst[n][k] = *(const PG8_LAS bf16x8*)(lds + PG8_SB(b, h) + boff + n * 2048 + k * 1024); } while (0)
; #define PG8_MMA(ai, bj, At, Bt) do { __builtin_amdgcn_s_setprio(1); _Pragma("unroll") for (int m = 0; m < 4; ++m) _Pragma("unroll") for (int n = 0; n < 2; ++n) _Pragma("unroll") for (int k = 0; k < 2; ++k) \
;         acc[ai][bj][m][n] = __builtin_amdgcn_mfma_f32_16x16x32_bf16(Bt[n][k], At[m][k], acc[ai][bj][m][n], 0, 0, 0); __builtin_amdgcn_s_setprio(0); } while (0)
; #define PG8_WAIT_V(n) asm volatile("s_waitcnt vmcnt(" #n ")" ::: "memory")
; #define PG8_WAIT_L(n) asm volatile("s_waitcnt lgkmcnt(" #n ")" ::: "memory")
; #define PG8_BAR __builtin_amdgcn_s_barrier()
; #define PG8_SCHED __builtin_amdgcn_sched_barrier(0)
; template <class Epi>
; __device__ __forceinline__ void gemm_phase(PG8_LAS unsigned char* lds, const Gemm g, const StaticOrder& S, const Epi& E) {
;     ...
;             PG8_LDB(B0, 0, 0); PG8_SCHED; PG8_LDA(At, 0, 0); PG8_STAGE(PG8_SA(1, 1), a1 + hstep, voffA);
;             PG8_WAIT_L(8); PG8_BAR; PG8_WAIT_L(0); PG8_MMA(0, 0, At, B0); PG8_BAR; PG8_SCHED;
;             PG8_LDB(B1, 0, 1); PG8_STAGE(PG8_SB(0, 0), b2, voffB);
;             PG8_BAR; PG8_WAIT_L(0); PG8_MMA(0, 1, At, B1); PG8_BAR;
;             PG8_LDA(At, 0, 1); PG8_STAGE(PG8_SA(0, 0), a2, voffA);
;             PG8_BAR; PG8_WAIT_L(0); PG8_MMA(1, 0, At, B0); PG8_BAR; PG8_SCHED;
;             PG8_STAGE(PG8_SB(0, 1), b2 + hstep, voffB);
;             PG8_WAIT_V(6); PG8_BAR; PG8_MMA(1, 1, At, B1); PG8_BAR;
.LBB0_1056:
	ds_read_b128 v[148:151], v155
	ds_read_b128 v[158:161], v155 offset:1024
	ds_read_b128 v[162:165], v155 offset:2048
	ds_read_b128 v[166:169], v155 offset:3072
	s_add_u32 s6, s4, 0xfff80080
	s_addc_u32 s7, s5, -1
	s_cmp_eq_u32 s56, 28
	s_cselect_b32 s31, s25, s7
	s_cselect_b32 s30, s52, s6
	s_cselect_b32 s7, s23, s55
	s_cselect_b32 s6, s53, s54
	v_lshl_add_u64 v[152:153], s[4:5], 0, v[140:141]
	s_add_i32 m0, s38, 0xc000
	ds_read_b128 v[170:173], v156
	ds_read_b128 v[174:177], v156 offset:1024
	ds_read_b128 v[178:181], v156 offset:2048
	ds_read_b128 v[182:185], v156 offset:3072
	ds_read_b128 v[186:189], v156 offset:4096
	ds_read_b128 v[190:193], v156 offset:5120
	ds_read_b128 v[194:197], v156 offset:6144
	ds_read_b128 v[198:201], v156 offset:7168
	global_load_lds_dwordx4 v[152:153], off
	v_lshl_add_u64 v[152:153], s[4:5], 0, v[142:143]
	s_add_i32 m0, s38, 0xe000
	s_nop 0
	global_load_lds_dwordx4 v[152:153], off
	s_waitcnt lgkmcnt(8)
	s_barrier
	s_waitcnt lgkmcnt(0)
	s_setprio 1
	s_waitcnt lgkmcnt(0)
	v_mfma_f32_16x16x32_bf16 v[126:129], v[148:151], v[170:173], v[126:129]
	v_mfma_f32_16x16x32_bf16 v[122:125], v[162:165], v[170:173], v[122:125]
	v_mfma_f32_16x16x32_bf16 v[110:113], v[148:151], v[178:181], v[110:113]
	v_mfma_f32_16x16x32_bf16 v[106:109], v[162:165], v[178:181], v[106:109]
	v_mfma_f32_16x16x32_bf16 v[94:97], v[148:151], v[186:189], v[94:97]
	v_mfma_f32_16x16x32_bf16 v[90:93], v[162:165], v[186:189], v[90:93]
	v_mfma_f32_16x16x32_bf16 v[78:81], v[148:151], v[194:197], v[78:81]
	v_mfma_f32_16x16x32_bf16 v[74:77], v[162:165], v[194:197], v[74:77]
	v_mfma_f32_16x16x32_bf16 v[126:129], v[158:161], v[174:177], v[126:129]
	v_mfma_f32_16x16x32_bf16 v[122:125], v[166:169], v[174:177], v[122:125]
	v_mfma_f32_16x16x32_bf16 v[110:113], v[158:161], v[182:185], v[110:113]
	v_mfma_f32_16x16x32_bf16 v[106:109], v[166:169], v[182:185], v[106:109]
	v_mfma_f32_16x16x32_bf16 v[94:97], v[158:161], v[190:193], v[94:97]
	v_mfma_f32_16x16x32_bf16 v[90:93], v[166:169], v[190:193], v[90:93]
	v_mfma_f32_16x16x32_bf16 v[78:81], v[158:161], v[198:201], v[78:81]
	v_mfma_f32_16x16x32_bf16 v[74:77], v[166:169], v[198:201], v[74:77]
	s_setprio 0
	s_barrier
	s_add_i32 s57, s46, s37
	v_lshl_add_u64 v[152:153], s[6:7], 0, v[134:135]
	s_mov_b32 m0, s57
	ds_read_b128 v[202:205], v157
	ds_read_b128 v[206:209], v157 offset:1024
	ds_read_b128 v[210:213], v157 offset:2048
	ds_read_b128 v[214:217], v157 offset:3072
	global_load_lds_dwordx4 v[152:153], off
	v_lshl_add_u64 v[218:219], s[6:7], 0, v[138:139]
	s_add_i32 m0, s57, 0x2000
	s_nop 0
	global_load_lds_dwordx4 v[218:219], off
	s_barrier
	s_waitcnt lgkmcnt(0)
	s_setprio 1
	s_waitcnt lgkmcnt(0)
	v_mfma_f32_16x16x32_bf16 v[118:121], v[202:205], v[170:173], v[118:121]
	v_mfma_f32_16x16x32_bf16 v[114:117], v[210:213], v[170:173], v[114:117]
	v_mfma_f32_16x16x32_bf16 v[102:105], v[202:205], v[178:181], v[102:105]
	v_mfma_f32_16x16x32_bf16 v[98:101], v[210:213], v[178:181], v[98:101]
	v_mfma_f32_16x16x32_bf16 v[86:89], v[202:205], v[186:189], v[86:89]
	v_mfma_f32_16x16x32_bf16 v[82:85], v[210:213], v[186:189], v[82:85]
	v_mfma_f32_16x16x32_bf16 v[70:73], v[202:205], v[194:197], v[70:73]
	v_mfma_f32_16x16x32_bf16 v[66:69], v[210:213], v[194:197], v[66:69]
	v_mfma_f32_16x16x32_bf16 v[118:121], v[206:209], v[174:177], v[118:121]
	v_mfma_f32_16x16x32_bf16 v[114:117], v[214:217], v[174:177], v[114:117]
	v_mfma_f32_16x16x32_bf16 v[102:105], v[206:209], v[182:185], v[102:105]
	v_mfma_f32_16x16x32_bf16 v[98:101], v[214:217], v[182:185], v[98:101]
	v_mfma_f32_16x16x32_bf16 v[86:89], v[206:209], v[190:193], v[86:89]
	v_mfma_f32_16x16x32_bf16 v[82:85], v[214:217], v[190:193], v[82:85]
	v_mfma_f32_16x16x32_bf16 v[70:73], v[206:209], v[198:201], v[70:73]
	v_mfma_f32_16x16x32_bf16 v[66:69], v[214:217], v[198:201], v[66:69]
	s_setprio 0
	s_mov_b32 m0, s38
	v_lshl_add_u64 v[220:221], s[30:31], 0, v[132:133]
	s_barrier
	ds_read_b128 v[170:173], v156 offset:16384
	ds_read_b128 v[174:177], v156 offset:17408
	ds_read_b128 v[178:181], v156 offset:18432
	ds_read_b128 v[182:185], v156 offset:19456
	ds_read_b128 v[186:189], v156 offset:20480
	ds_read_b128 v[190:193], v156 offset:21504
	ds_read_b128 v[194:197], v156 offset:22528
	ds_read_b128 v[198:201], v156 offset:23552
	global_load_lds_dwordx4 v[220:221], off
	v_lshl_add_u64 v[222:223], s[30:31], 0, v[136:137]
	s_mov_b32 m0, s39
	s_nop 0
	global_load_lds_dwordx4 v[222:223], off
	s_barrier
	s_waitcnt lgkmcnt(0)
	s_setprio 1
	s_waitcnt lgkmcnt(0)
	v_mfma_f32_16x16x32_bf16 v[62:65], v[148:151], v[170:173], v[62:65]
	v_mfma_f32_16x16x32_bf16 v[58:61], v[162:165], v[170:173], v[58:61]
	v_mfma_f32_16x16x32_bf16 v[46:49], v[148:151], v[178:181], v[46:49]
	v_mfma_f32_16x16x32_bf16 v[42:45], v[162:165], v[178:181], v[42:45]
	v_mfma_f32_16x16x32_bf16 v[30:33], v[148:151], v[186:189], v[30:33]
	v_mfma_f32_16x16x32_bf16 v[26:29], v[162:165], v[186:189], v[26:29]
	v_mfma_f32_16x16x32_bf16 v[14:17], v[148:151], v[194:197], v[14:17]
	v_mfma_f32_16x16x32_bf16 v[10:13], v[162:165], v[194:197], v[10:13]
	v_mfma_f32_16x16x32_bf16 v[62:65], v[158:161], v[174:177], v[62:65]
	v_mfma_f32_16x16x32_bf16 v[58:61], v[166:169], v[174:177], v[58:61]
	v_mfma_f32_16x16x32_bf16 v[46:49], v[158:161], v[182:185], v[46:49]
	v_mfma_f32_16x16x32_bf16 v[42:45], v[166:169], v[182:185], v[42:45]
	v_mfma_f32_16x16x32_bf16 v[30:33], v[158:161], v[190:193], v[30:33]
	v_mfma_f32_16x16x32_bf16 v[26:29], v[166:169], v[190:193], v[26:29]
	v_mfma_f32_16x16x32_bf16 v[14:17], v[158:161], v[198:201], v[14:17]
	v_mfma_f32_16x16x32_bf16 v[10:13], v[166:169], v[198:201], v[10:13]
	s_setprio 0
	s_barrier
; #define PG8_STAGE(bufoff, gbase, voff) do { _Pragma("unroll") for (int _i = 0; _i < 2; ++_i) \
;         __builtin_amdgcn_global_load_lds((const unsigned*)((const char*)(gbase) + (voff)[_i]), (PG8_LAS unsigned*)(lds + (bufoff) + ldsw + _i * 8192), 16, 0, 0); } while (0)
; #define PG8_LDA(dst, b, h) do { _Pragma("unroll") for (int m = 0; m < 4; ++m) _Pragma("unroll") for (int k = 0; k < 2; ++k) dst[m][k] = *(const PG8_LAS bf16x8*)(lds + PG8_SA(b, h) + aoff + m * 2048 + k * 1024); } while (0)
; #define PG8_LDB(dst, b, h) do { _Pragma("unroll") for (int n = 0; n < 2; ++n) _Pragma("unroll") for (int k = 0; k < 2; ++k) dst[n][k] = *(const PG8_LAS bf16x8*)(lds + PG8_SB(b, h) + boff + n * 2048 + k * 1024); } while (0)
; #define PG8_MMA(ai, bj, At, Bt) do { __builtin_amdgcn_s_setprio(1); _Pragma("unroll") for (int m = 0; m < 4; ++m) _Pragma("unroll") for (int n = 0; n < 2; ++n) _Pragma("unroll") for (int k = 0; k < 2; ++k) \
;         acc[ai][bj][m][n] = __builtin_amdgcn_mfma_f32_16x16x32_bf16(Bt[n][k], At[m][k], acc[ai][bj][m][n], 0, 0, 0); __builtin_amdgcn_s_setprio(0); } while (0)
; #define PG8_WAIT_V(n) asm volatile("s_waitcnt vmcnt(" #n ")" ::: "memory")
; #define PG8_WAIT_L(n) asm volatile("s_waitcnt lgkmcnt(" #n ")" ::: "memory")
; #define PG8_BAR __builtin_amdgcn_s_barrier()
; #define PG8_SCHED __builtin_amdgcn_sched_barrier(0)
; template <class Epi>
; __device__ __forceinline__ void gemm_phase(PG8_LAS unsigned char* lds, const Gemm g, const StaticOrder& S, const Epi& E) {
;     ...
;             PG8_WAIT_V(6); PG8_BAR; PG8_MMA(1, 1, At, B1); PG8_BAR;
;             PG8_LDB(B0, 1, 0); PG8_SCHED; PG8_LDA(At, 1, 0); PG8_STAGE(PG8_SA(0, 1), a2 + hstep, voffA);
;             PG8_WAIT_L(8); PG8_BAR; PG8_WAIT_L(0); PG8_MMA(0, 0, At, B0); PG8_BAR; PG8_SCHED;
;             PG8_LDB(B1, 1, 1); PG8_STAGE(PG8_SB(1, 0), b3, voffB);
;             PG8_BAR; PG8_WAIT_L(0); PG8_MMA(0, 1, At, B1); PG8_BAR;
;             PG8_LDA(At, 1, 1); PG8_STAGE(PG8_SA(1, 0), a3, voffA);
;             PG8_BAR; PG8_WAIT_L(0); PG8_MMA(1, 0, At, B0); PG8_BAR; PG8_SCHED;
	s_add_u32 s58, s6, 0x80000
	s_addc_u32 s59, s7, 0
	s_add_i32 s57, s47, s37
	v_lshl_add_u64 v[148:149], s[58:59], 0, v[134:135]
	s_mov_b32 m0, s57
	s_nop 0
	global_load_lds_dwordx4 v[148:149], off
	v_lshl_add_u64 v[148:149], s[58:59], 0, v[138:139]
	s_add_i32 m0, s57, 0x2000
	s_nop 0
	global_load_lds_dwordx4 v[148:149], off
	s_waitcnt vmcnt(6)
	s_barrier
	s_setprio 1
	v_mfma_f32_16x16x32_bf16 v[54:57], v[202:205], v[170:173], v[54:57]
	v_mfma_f32_16x16x32_bf16 v[50:53], v[210:213], v[170:173], v[50:53]
	v_mfma_f32_16x16x32_bf16 v[38:41], v[202:205], v[178:181], v[38:41]
	v_mfma_f32_16x16x32_bf16 v[34:37], v[210:213], v[178:181], v[34:37]
	v_mfma_f32_16x16x32_bf16 v[22:25], v[202:205], v[186:189], v[22:25]
	v_mfma_f32_16x16x32_bf16 v[18:21], v[210:213], v[186:189], v[18:21]
	v_mfma_f32_16x16x32_bf16 v[6:9], v[202:205], v[194:197], v[6:9]
	v_mfma_f32_16x16x32_bf16 v[2:5], v[210:213], v[194:197], v[2:5]
	v_mfma_f32_16x16x32_bf16 v[54:57], v[206:209], v[174:177], v[54:57]
	v_mfma_f32_16x16x32_bf16 v[50:53], v[214:217], v[174:177], v[50:53]
	v_mfma_f32_16x16x32_bf16 v[38:41], v[206:209], v[182:185], v[38:41]
	v_mfma_f32_16x16x32_bf16 v[34:37], v[214:217], v[182:185], v[34:37]
	v_mfma_f32_16x16x32_bf16 v[22:25], v[206:209], v[190:193], v[22:25]
	v_mfma_f32_16x16x32_bf16 v[18:21], v[214:217], v[190:193], v[18:21]
	v_mfma_f32_16x16x32_bf16 v[6:9], v[206:209], v[198:201], v[6:9]
	v_mfma_f32_16x16x32_bf16 v[2:5], v[214:217], v[198:201], v[2:5]
	s_setprio 0
	s_add_i32 s57, 0, 0x18000
	v_add_u32_e32 v166, s57, v131
	s_barrier
	ds_read_b128 v[148:151], v166
	ds_read_b128 v[158:161], v166 offset:1024
	ds_read_b128 v[162:165], v166 offset:2048
	ds_read_b128 v[166:169], v166 offset:3072
	s_add_u32 s30, s30, 0x80000
	s_addc_u32 s31, s31, 0
	s_mov_b32 m0, s40
	v_lshl_add_u64 v[202:203], s[30:31], 0, v[132:133]
	ds_read_b128 v[170:173], v156 offset:32768
	ds_read_b128 v[174:177], v156 offset:33792
	ds_read_b128 v[178:181], v156 offset:34816
	ds_read_b128 v[182:185], v156 offset:35840
	ds_read_b128 v[186:189], v156 offset:36864
	ds_read_b128 v[190:193], v156 offset:37888
	ds_read_b128 v[194:197], v156 offset:38912
	ds_read_b128 v[198:201], v156 offset:39936
	global_load_lds_dwordx4 v[202:203], off
	v_lshl_add_u64 v[202:203], s[30:31], 0, v[136:137]
	s_mov_b32 m0, s41
	s_nop 0
	global_load_lds_dwordx4 v[202:203], off
	s_waitcnt lgkmcnt(8)
	s_barrier
	s_waitcnt lgkmcnt(0)
	s_setprio 1
	s_waitcnt lgkmcnt(0)
	v_mfma_f32_16x16x32_bf16 v[126:129], v[148:151], v[170:173], v[126:129]
	v_mfma_f32_16x16x32_bf16 v[122:125], v[162:165], v[170:173], v[122:125]
	v_mfma_f32_16x16x32_bf16 v[110:113], v[148:151], v[178:181], v[110:113]
	v_mfma_f32_16x16x32_bf16 v[106:109], v[162:165], v[178:181], v[106:109]
	v_mfma_f32_16x16x32_bf16 v[94:97], v[148:151], v[186:189], v[94:97]
	v_mfma_f32_16x16x32_bf16 v[90:93], v[162:165], v[186:189], v[90:93]
	v_mfma_f32_16x16x32_bf16 v[78:81], v[148:151], v[194:197], v[78:81]
	v_mfma_f32_16x16x32_bf16 v[74:77], v[162:165], v[194:197], v[74:77]
	v_mfma_f32_16x16x32_bf16 v[126:129], v[158:161], v[174:177], v[126:129]
	v_mfma_f32_16x16x32_bf16 v[122:125], v[166:169], v[174:177], v[122:125]
	v_mfma_f32_16x16x32_bf16 v[110:113], v[158:161], v[182:185], v[110:113]
	v_mfma_f32_16x16x32_bf16 v[106:109], v[166:169], v[182:185], v[106:109]
	v_mfma_f32_16x16x32_bf16 v[94:97], v[158:161], v[190:193], v[94:97]
	v_mfma_f32_16x16x32_bf16 v[90:93], v[166:169], v[190:193], v[90:93]
	v_mfma_f32_16x16x32_bf16 v[78:81], v[158:161], v[198:201], v[78:81]
	v_mfma_f32_16x16x32_bf16 v[74:77], v[166:169], v[198:201], v[74:77]
	s_setprio 0
	s_barrier
	s_add_i32 s30, 0, 0x1c000
	s_add_i32 s31, s57, s37
	v_add_u32_e32 v214, s30, v131
	v_lshl_add_u64 v[152:153], v[152:153], 0, s[12:13]
	s_mov_b32 m0, s31
	ds_read_b128 v[202:205], v214
	ds_read_b128 v[206:209], v214 offset:1024
	ds_read_b128 v[210:213], v214 offset:2048
	ds_read_b128 v[214:217], v214 offset:3072
	global_load_lds_dwordx4 v[152:153], off
	v_lshl_add_u64 v[152:153], v[218:219], 0, s[12:13]
	s_add_i32 m0, s31, 0x2000
	s_nop 0
	global_load_lds_dwordx4 v[152:153], off
	s_barrier
	s_waitcnt lgkmcnt(0)
	s_setprio 1
	s_waitcnt lgkmcnt(0)
	v_mfma_f32_16x16x32_bf16 v[118:121], v[202:205], v[170:173], v[118:121]
	v_mfma_f32_16x16x32_bf16 v[114:117], v[210:213], v[170:173], v[114:117]
	v_mfma_f32_16x16x32_bf16 v[102:105], v[202:205], v[178:181], v[102:105]
	v_mfma_f32_16x16x32_bf16 v[98:101], v[210:213], v[178:181], v[98:101]
	v_mfma_f32_16x16x32_bf16 v[86:89], v[202:205], v[186:189], v[86:89]
	v_mfma_f32_16x16x32_bf16 v[82:85], v[210:213], v[186:189], v[82:85]
	v_mfma_f32_16x16x32_bf16 v[70:73], v[202:205], v[194:197], v[70:73]
	v_mfma_f32_16x16x32_bf16 v[66:69], v[210:213], v[194:197], v[66:69]
	v_mfma_f32_16x16x32_bf16 v[118:121], v[206:209], v[174:177], v[118:121]
	v_mfma_f32_16x16x32_bf16 v[114:117], v[214:217], v[174:177], v[114:117]
	v_mfma_f32_16x16x32_bf16 v[102:105], v[206:209], v[182:185], v[102:105]
	v_mfma_f32_16x16x32_bf16 v[98:101], v[214:217], v[182:185], v[98:101]
	v_mfma_f32_16x16x32_bf16 v[86:89], v[206:209], v[190:193], v[86:89]
	v_mfma_f32_16x16x32_bf16 v[82:85], v[214:217], v[190:193], v[82:85]
	v_mfma_f32_16x16x32_bf16 v[70:73], v[206:209], v[198:201], v[70:73]
	v_mfma_f32_16x16x32_bf16 v[66:69], v[214:217], v[198:201], v[66:69]
	s_setprio 0
	s_mov_b32 m0, s43
	v_lshl_add_u64 v[152:153], v[220:221], 0, s[12:13]
	s_barrier
	ds_read_b128 v[170:173], v156 offset:49152
	ds_read_b128 v[174:177], v156 offset:50176
	ds_read_b128 v[178:181], v156 offset:51200
	ds_read_b128 v[182:185], v156 offset:52224
	ds_read_b128 v[186:189], v156 offset:53248
	ds_read_b128 v[190:193], v156 offset:54272
	ds_read_b128 v[194:197], v156 offset:55296
	ds_read_b128 v[198:201], v156 offset:56320
	global_load_lds_dwordx4 v[152:153], off
	v_lshl_add_u64 v[152:153], v[222:223], 0, s[12:13]
	s_mov_b32 m0, s44
	s_nop 0
	global_load_lds_dwordx4 v[152:153], off
	s_barrier
; #define PG8_STAGE(bufoff, gbase, voff) do { _Pragma("unroll") for (int _i = 0; _i < 2; ++_i) \
;         __builtin_amdgcn_global_load_lds((const unsigned*)((const char*)(gbase) + (voff)[_i]), (PG8_LAS unsigned*)(lds + (bufoff) + ldsw + _i * 8192), 16, 0, 0); } while (0)
; #define PG8_MMA(ai, bj, At, Bt) do { __builtin_amdgcn_s_setprio(1); _Pragma("unroll") for (int m = 0; m < 4; ++m) _Pragma("unroll") for (int n = 0; n < 2; ++n) _Pragma("unroll") for (int k = 0; k < 2; ++k) \
;         acc[ai][bj][m][n] = __builtin_amdgcn_mfma_f32_16x16x32_bf16(Bt[n][k], At[m][k], acc[ai][bj][m][n], 0, 0, 0); __builtin_amdgcn_s_setprio(0); } while (0)
; #define PG8_WAIT_V(n) asm volatile("s_waitcnt vmcnt(" #n ")" ::: "memory")
; #define PG8_BAR __builtin_amdgcn_s_barrier()
; template <class Epi>
; __device__ __forceinline__ void gemm_phase(PG8_LAS unsigned char* lds, const Gemm g, const StaticOrder& S, const Epi& E) {
;     ...
;             PG8_STAGE(PG8_SB(1, 1), b3 + hstep, voffB);
;             PG8_WAIT_V(6); PG8_BAR; PG8_MMA(1, 1, At, B1); PG8_BAR;
;         }
;         E(acc, cur, wr, wc, fr, fq);
	s_waitcnt lgkmcnt(0)
	s_setprio 1
	s_waitcnt lgkmcnt(0)
	v_mfma_f32_16x16x32_bf16 v[62:65], v[148:151], v[170:173], v[62:65]
	v_mfma_f32_16x16x32_bf16 v[58:61], v[162:165], v[170:173], v[58:61]
	v_mfma_f32_16x16x32_bf16 v[46:49], v[148:151], v[178:181], v[46:49]
	v_mfma_f32_16x16x32_bf16 v[42:45], v[162:165], v[178:181], v[42:45]
	v_mfma_f32_16x16x32_bf16 v[30:33], v[148:151], v[186:189], v[30:33]
	v_mfma_f32_16x16x32_bf16 v[26:29], v[162:165], v[186:189], v[26:29]
	v_mfma_f32_16x16x32_bf16 v[14:17], v[148:151], v[194:197], v[14:17]
	v_mfma_f32_16x16x32_bf16 v[10:13], v[162:165], v[194:197], v[10:13]
	v_mfma_f32_16x16x32_bf16 v[62:65], v[158:161], v[174:177], v[62:65]
	v_mfma_f32_16x16x32_bf16 v[58:61], v[166:169], v[174:177], v[58:61]
	v_mfma_f32_16x16x32_bf16 v[46:49], v[158:161], v[182:185], v[46:49]
	v_mfma_f32_16x16x32_bf16 v[42:45], v[166:169], v[182:185], v[42:45]
	v_mfma_f32_16x16x32_bf16 v[30:33], v[158:161], v[190:193], v[30:33]
	v_mfma_f32_16x16x32_bf16 v[26:29], v[166:169], v[190:193], v[26:29]
	v_mfma_f32_16x16x32_bf16 v[14:17], v[158:161], v[198:201], v[14:17]
	v_mfma_f32_16x16x32_bf16 v[10:13], v[166:169], v[198:201], v[10:13]
	s_setprio 0
	s_barrier
	s_add_u32 s6, s6, 0x80080
	s_addc_u32 s7, s7, 0
	s_add_i32 s30, s30, s37
	v_lshl_add_u64 v[148:149], s[6:7], 0, v[134:135]
	s_mov_b32 m0, s30
	s_nop 0
	global_load_lds_dwordx4 v[148:149], off
	v_lshl_add_u64 v[148:149], s[6:7], 0, v[138:139]
	s_add_i32 m0, s30, 0x2000
	s_nop 0
	global_load_lds_dwordx4 v[148:149], off
	s_waitcnt vmcnt(6)
	s_barrier
	s_setprio 1
	v_mfma_f32_16x16x32_bf16 v[54:57], v[202:205], v[170:173], v[54:57]
	v_mfma_f32_16x16x32_bf16 v[50:53], v[210:213], v[170:173], v[50:53]
	v_mfma_f32_16x16x32_bf16 v[38:41], v[202:205], v[178:181], v[38:41]
	v_mfma_f32_16x16x32_bf16 v[34:37], v[210:213], v[178:181], v[34:37]
	v_mfma_f32_16x16x32_bf16 v[22:25], v[202:205], v[186:189], v[22:25]
	v_mfma_f32_16x16x32_bf16 v[18:21], v[210:213], v[186:189], v[18:21]
	v_mfma_f32_16x16x32_bf16 v[6:9], v[202:205], v[194:197], v[6:9]
	v_mfma_f32_16x16x32_bf16 v[2:5], v[210:213], v[194:197], v[2:5]
	v_mfma_f32_16x16x32_bf16 v[54:57], v[206:209], v[174:177], v[54:57]
	v_mfma_f32_16x16x32_bf16 v[50:53], v[214:217], v[174:177], v[50:53]
	v_mfma_f32_16x16x32_bf16 v[38:41], v[206:209], v[182:185], v[38:41]
	v_mfma_f32_16x16x32_bf16 v[34:37], v[214:217], v[182:185], v[34:37]
	v_mfma_f32_16x16x32_bf16 v[22:25], v[206:209], v[190:193], v[22:25]
	v_mfma_f32_16x16x32_bf16 v[18:21], v[214:217], v[190:193], v[18:21]
	v_mfma_f32_16x16x32_bf16 v[6:9], v[206:209], v[198:201], v[6:9]
	v_mfma_f32_16x16x32_bf16 v[2:5], v[214:217], v[198:201], v[2:5]
	s_setprio 0
	s_add_i32 s56, s56, 2
	s_add_u32 s4, s4, 0x100
	s_addc_u32 s5, s5, 0
	s_add_u32 s54, s54, 0x100
	s_addc_u32 s55, s55, 0
	s_cmp_gt_u32 s56, 29
	s_barrier
	s_cbranch_scc0 .LBB0_1056
	v_lshl_add_u32 v150, s2, 8, v1
	v_lshl_or_b32 v148, s3, 8, v154
	v_ashrrev_i32_e32 v151, 31, v150
	v_lshlrev_b64 v[152:153], 13, v[150:151]
	v_ashrrev_i32_e32 v149, 31, v148
	v_lshl_add_u64 v[158:159], s[10:11], 0, v[152:153]
	v_lshlrev_b64 v[152:153], 1, v[148:149]
	v_lshl_add_u64 v[148:149], v[158:159], 0, v[152:153]
	s_mov_b64 s[98:99], 0x20000
	global_load_dwordx4 v[186:189], v[148:149], off
	global_load_dwordx4 v[190:193], v[148:149], off offset:256
	v_lshl_add_u64 v[252:253], v[148:149], 0, s[98:99]
	global_load_dwordx4 v[194:197], v[252:253], off
	global_load_dwordx4 v[198:201], v[252:253], off offset:256
	v_lshl_add_u64 v[254:255], v[252:253], 0, s[98:99]
	global_load_dwordx4 v[202:205], v[254:255], off
	global_load_dwordx4 v[206:209], v[254:255], off offset:256
	v_lshl_add_u64 v[252:253], v[254:255], 0, s[98:99]
	global_load_dwordx4 v[210:213], v[252:253], off
	global_load_dwordx4 v[214:217], v[252:253], off offset:256
	v_lshl_add_u64 v[254:255], v[148:149], 0, s[14:15]
	global_load_dwordx4 v[218:221], v[254:255], off
	global_load_dwordx4 v[222:225], v[254:255], off offset:256
	v_lshl_add_u64 v[252:253], v[148:149], 0, s[16:17]
	global_load_dwordx4 v[226:229], v[252:253], off
	global_load_dwordx4 v[230:233], v[252:253], off offset:256
	v_lshl_add_u64 v[254:255], v[148:149], 0, s[18:19]
	global_load_dwordx4 v[234:237], v[254:255], off
	global_load_dwordx4 v[238:241], v[254:255], off offset:256
	v_lshl_add_u64 v[252:253], v[148:149], 0, s[20:21]
	global_load_dwordx4 v[242:245], v[252:253], off
	global_load_dwordx4 v[246:249], v[252:253], off offset:256
	v_mul_f32_e32 v151, 0xbfb8aa3b, v126
	v_mul_f32_e32 v162, 0xbfb8aa3b, v122
	v_exp_f32_e32 v151, v151
	v_mul_f32_e32 v163, 0xbfb8aa3b, v127
	v_exp_f32_e32 v162, v162
	v_exp_f32_e32 v163, v163
	v_add_f32_e32 v151, 1.0, v151
	v_div_scale_f32 v166, s[2:3], v151, v151, v126
	v_add_f32_e32 v162, 1.0, v162
	v_add_f32_e32 v163, 1.0, v163
	v_div_scale_f32 v168, s[2:3], v162, v162, v122
	v_rcp_f32_e32 v174, v166
	v_mul_f32_e32 v164, 0xbfb8aa3b, v123
	v_div_scale_f32 v170, s[4:5], v163, v163, v127
	v_rcp_f32_e32 v175, v168
	v_exp_f32_e32 v164, v164
	v_rcp_f32_e32 v176, v170
	v_fma_f32 v178, -v166, v174, 1.0
	v_div_scale_f32 v167, vcc, v126, v151, v126
	v_fma_f32 v179, -v168, v175, 1.0
	v_fmac_f32_e32 v174, v178, v174
	v_add_f32_e32 v164, 1.0, v164
	v_div_scale_f32 v169, s[2:3], v122, v162, v122
	v_fma_f32 v180, -v170, v176, 1.0
	v_fmac_f32_e32 v175, v179, v175
	v_mul_f32_e32 v178, v167, v174
	v_div_scale_f32 v171, s[4:5], v127, v163, v127
	v_div_scale_f32 v172, s[6:7], v164, v164, v123
	v_fmac_f32_e32 v176, v180, v176
	v_mul_f32_e32 v179, v169, v175
	v_fma_f32 v182, -v166, v178, v167
	v_rcp_f32_e32 v177, v172
	v_mul_f32_e32 v180, v171, v176
	v_fma_f32 v183, -v168, v179, v169
	v_fmac_f32_e32 v178, v182, v174
	v_mul_f32_e32 v165, 0xbfb8aa3b, v128
	v_fma_f32 v184, -v170, v180, v171
	v_fmac_f32_e32 v179, v183, v175
	v_fma_f32 v166, -v166, v178, v167
	v_exp_f32_e32 v165, v165
	v_fmac_f32_e32 v180, v184, v176
	v_fma_f32 v167, -v168, v179, v169
	v_div_fmas_f32 v166, v166, v174, v178
	s_mov_b64 vcc, s[2:3]
	v_fma_f32 v168, -v170, v180, v171
	v_div_fixup_f32 v126, v166, v151, v126
	v_div_fmas_f32 v151, v167, v175, v179
	s_mov_b64 vcc, s[4:5]
	v_fma_f32 v181, -v172, v177, 1.0
	v_div_fixup_f32 v122, v151, v162, v122
	v_div_fmas_f32 v151, v168, v176, v180
	v_div_scale_f32 v173, s[6:7], v123, v164, v123
	v_fmac_f32_e32 v177, v181, v177
	v_div_fixup_f32 v127, v151, v163, v127
	v_mul_f32_e32 v181, v173, v177
	v_fma_f32 v185, -v172, v181, v173
	v_fmac_f32_e32 v181, v185, v177
	v_fma_f32 v169, -v172, v181, v173
	s_mov_b64 vcc, s[6:7]
	s_mov_b64 s[6:7], s[28:29]
	s_mov_b64 s[4:5], s[26:27]
	s_waitcnt vmcnt(14)
;     __device__ __forceinline__ void operator()(const f32x4 (&acc)[2][2][4][2], const Unit& u, int wr, int wc, int fr, int fq) const {
;         const int row0 = u.pm * BM + wr * 64 + fr, col0 = u.pn * BM + wc * 32 + 8 * fq;
; #pragma unroll
;         for (int ai = 0; ai < 2; ++ai)
; #pragma unroll
;             for (int m = 0; m < 4; ++m)
; #pragma unroll
;                 for (int bj = 0; bj < 2; ++bj) f(row0 + ai * HALF + m * 16, col0 + bj * HALF, acc[ai][bj][m][0], acc[ai][bj][m][1]);
	v_mov_b32_e32 v158, v186
	v_mov_b32_e32 v159, v187
	v_mov_b32_e32 v160, v188
	v_mov_b32_e32 v161, v189
	v_lshlrev_b32_e32 v151, 16, v158
	v_and_b32_e32 v158, 0xffff0000, v158
	v_lshlrev_b32_e32 v163, 16, v160
	v_mul_f32_e32 v126, v126, v151
	v_mul_f32_e32 v151, v122, v163
	v_mul_f32_e32 v122, v127, v158
	v_add_f32_e32 v127, 1.0, v165
	v_div_scale_f32 v158, s[2:3], v127, v127, v128
	v_rcp_f32_e32 v163, v158
	v_div_fmas_f32 v165, v169, v177, v181
	v_and_b32_e32 v160, 0xffff0000, v160
	v_div_fixup_f32 v123, v165, v164, v123
	v_mul_f32_e32 v160, v123, v160
	v_fma_f32 v123, -v158, v163, 1.0
	v_mul_f32_e32 v165, 0xbfb8aa3b, v124
	v_fmac_f32_e32 v163, v123, v163
	v_div_scale_f32 v123, vcc, v128, v127, v128
	v_exp_f32_e32 v165, v165
	v_mul_f32_e32 v164, v123, v163
	v_fma_f32 v167, -v158, v164, v123
	v_fmac_f32_e32 v164, v167, v163
	v_fma_f32 v123, -v158, v164, v123
	v_add_f32_e32 v158, 1.0, v165
	v_div_scale_f32 v165, s[2:3], v158, v158, v124
	v_rcp_f32_e32 v167, v165
	v_div_fmas_f32 v123, v123, v163, v164
	v_lshlrev_b32_e32 v162, 16, v159
	v_div_fixup_f32 v123, v123, v127, v128
	v_mul_f32_e32 v123, v123, v162
	v_mul_f32_e32 v162, 0xbfb8aa3b, v129
	v_exp_f32_e32 v162, v162
	v_fma_f32 v127, -v165, v167, 1.0
	v_fmac_f32_e32 v167, v127, v167
	v_div_scale_f32 v127, vcc, v124, v158, v124
	v_mul_f32_e32 v128, v127, v167
	v_fma_f32 v163, -v165, v128, v127
	v_add_f32_e32 v162, 1.0, v162
	v_fmac_f32_e32 v128, v163, v167
	v_div_scale_f32 v163, s[2:3], v162, v162, v129
	v_rcp_f32_e32 v164, v163
	v_fma_f32 v127, -v165, v128, v127
	v_div_fmas_f32 v127, v127, v167, v128
	v_lshlrev_b32_e32 v166, 16, v161
	v_div_fixup_f32 v124, v127, v158, v124
	v_mul_f32_e32 v158, 0xbfb8aa3b, v125
	v_mul_f32_e32 v127, v124, v166
	v_fma_f32 v124, -v163, v164, 1.0
	v_exp_f32_e32 v158, v158
	v_fmac_f32_e32 v164, v124, v164
	v_div_scale_f32 v124, vcc, v129, v162, v129
	v_mul_f32_e32 v128, v124, v164
	v_fma_f32 v165, -v163, v128, v124
	v_fmac_f32_e32 v128, v165, v164
	v_add_f32_e32 v158, 1.0, v158
	v_fma_f32 v124, -v163, v128, v124
	v_div_scale_f32 v163, s[2:3], v158, v158, v125
	v_rcp_f32_e32 v165, v163
	v_div_fmas_f32 v124, v124, v164, v128
	v_and_b32_e32 v159, 0xffff0000, v159
	v_div_fixup_f32 v124, v124, v162, v129
	v_fma_f32 v128, -v163, v165, 1.0
	v_fmac_f32_e32 v165, v128, v165
	v_div_scale_f32 v128, vcc, v125, v158, v125
	v_mul_f32_e32 v129, v128, v165
	v_mul_f32_e32 v124, v124, v159
	v_fma_f32 v159, -v163, v129, v128
	v_fmac_f32_e32 v129, v159, v165
	v_fma_f32 v128, -v163, v129, v128
	v_div_fmas_f32 v128, v128, v165, v129
	v_and_b32_e32 v161, 0xffff0000, v161
	v_div_fixup_f32 v125, v128, v158, v125
	v_mul_f32_e32 v125, v125, v161
	v_cvt_pk_bf16_f32 v122, v126, v122
	v_cvt_pk_bf16_f32 v123, v123, v124
	v_cvt_pk_bf16_f32 v124, v151, v160
	v_cvt_pk_bf16_f32 v125, v127, v125
	v_mul_f32_e32 v162, 0xbfb8aa3b, v114
	global_store_dwordx4 v[148:149], v[122:125], off
	v_exp_f32_e32 v162, v162
	s_waitcnt vmcnt(14)
	v_mov_b32_e32 v126, v190
	v_mov_b32_e32 v127, v191
	v_mov_b32_e32 v128, v192
	v_mov_b32_e32 v129, v193
	v_lshlrev_b32_e32 v159, 16, v129
	v_mul_f32_e32 v124, 0xbfb8aa3b, v118
	v_exp_f32_e32 v124, v124
	v_lshlrev_b32_e32 v122, 16, v126
	v_and_b32_e32 v123, 0xffff0000, v126
	v_lshlrev_b32_e32 v125, 16, v127
	v_add_f32_e32 v124, 1.0, v124
	v_div_scale_f32 v151, s[2:3], v124, v124, v118
	v_rcp_f32_e32 v158, v151
	v_and_b32_e32 v126, 0xffff0000, v127
	v_lshlrev_b32_e32 v127, 16, v128
	v_and_b32_e32 v128, 0xffff0000, v128
	v_fma_f32 v160, -v151, v158, 1.0
	v_fmac_f32_e32 v158, v160, v158
	v_div_scale_f32 v160, vcc, v118, v124, v118
	v_mul_f32_e32 v161, v160, v158
	v_fma_f32 v163, -v151, v161, v160
	v_fmac_f32_e32 v161, v163, v158
	v_fma_f32 v151, -v151, v161, v160
	v_add_f32_e32 v160, 1.0, v162
	v_div_scale_f32 v162, s[2:3], v160, v160, v114
	v_rcp_f32_e32 v163, v162
	v_div_fmas_f32 v151, v151, v158, v161
	v_div_fixup_f32 v118, v151, v124, v118
	v_mul_f32_e32 v151, 0xbfb8aa3b, v119
	v_exp_f32_e32 v151, v151
	v_mul_f32_e32 v118, v118, v122
	v_fma_f32 v122, -v162, v163, 1.0
	v_fmac_f32_e32 v163, v122, v163
	v_div_scale_f32 v122, vcc, v114, v160, v114
	v_mul_f32_e32 v124, v122, v163
	v_fma_f32 v158, -v162, v124, v122
	v_add_f32_e32 v151, 1.0, v151
	v_fmac_f32_e32 v124, v158, v163
	v_div_scale_f32 v158, s[2:3], v151, v151, v119
	v_fma_f32 v122, -v162, v124, v122
	v_rcp_f32_e32 v161, v158
	v_div_fmas_f32 v122, v122, v163, v124
	v_div_fixup_f32 v114, v122, v160, v114
	v_mul_f32_e32 v114, v114, v127
	v_mul_f32_e32 v127, 0xbfb8aa3b, v115
	v_fma_f32 v122, -v158, v161, 1.0
	v_exp_f32_e32 v127, v127
	v_fmac_f32_e32 v161, v122, v161
	v_div_scale_f32 v122, vcc, v119, v151, v119
	v_mul_f32_e32 v124, v122, v161
	v_fma_f32 v160, -v158, v124, v122
	v_fmac_f32_e32 v124, v160, v161
	v_add_f32_e32 v127, 1.0, v127
	v_fma_f32 v122, -v158, v124, v122
	v_div_scale_f32 v158, s[2:3], v127, v127, v115
	v_rcp_f32_e32 v160, v158
	v_div_fmas_f32 v122, v122, v161, v124
	v_mul_f32_e32 v124, 0xbfb8aa3b, v120
	v_exp_f32_e32 v124, v124
	v_div_fixup_f32 v119, v122, v151, v119
	v_fma_f32 v122, -v158, v160, 1.0
	v_fmac_f32_e32 v160, v122, v160
	v_div_scale_f32 v122, vcc, v115, v127, v115
	v_mul_f32_e32 v119, v119, v123
	v_mul_f32_e32 v123, v122, v160
	v_fma_f32 v151, -v158, v123, v122
	v_add_f32_e32 v124, 1.0, v124
	v_fmac_f32_e32 v123, v151, v160
	v_div_scale_f32 v151, s[2:3], v124, v124, v120
	v_fma_f32 v122, -v158, v123, v122
	v_rcp_f32_e32 v158, v151
	v_div_fmas_f32 v122, v122, v160, v123
	v_div_fixup_f32 v115, v122, v127, v115
	v_mul_f32_e32 v127, 0xbfb8aa3b, v116
	v_exp_f32_e32 v127, v127
	v_fma_f32 v122, -v151, v158, 1.0
	v_fmac_f32_e32 v158, v122, v158
	v_div_scale_f32 v122, vcc, v120, v124, v120
;     __device__ __forceinline__ void operator()(const f32x4 (&acc)[2][2][4][2], const Unit& u, int wr, int wc, int fr, int fq) const {
;         const int row0 = u.pm * BM + wr * 64 + fr, col0 = u.pn * BM + wc * 32 + 8 * fq;
; #pragma unroll
;         for (int ai = 0; ai < 2; ++ai)
; #pragma unroll
;             for (int m = 0; m < 4; ++m)
; #pragma unroll
;                 for (int bj = 0; bj < 2; ++bj) f(row0 + ai * HALF + m * 16, col0 + bj * HALF, acc[ai][bj][m][0], acc[ai][bj][m][1]);
	v_mul_f32_e32 v123, v122, v158
	v_mul_f32_e32 v115, v115, v128
	v_fma_f32 v128, -v151, v123, v122
	v_add_f32_e32 v127, 1.0, v127
	v_fmac_f32_e32 v123, v128, v158
	v_div_scale_f32 v128, s[2:3], v127, v127, v116
	v_fma_f32 v122, -v151, v123, v122
	v_rcp_f32_e32 v151, v128
	v_div_fmas_f32 v122, v122, v158, v123
	v_div_fixup_f32 v120, v122, v124, v120
	v_mul_f32_e32 v124, 0xbfb8aa3b, v121
	v_exp_f32_e32 v124, v124
	v_fma_f32 v122, -v128, v151, 1.0
	v_fmac_f32_e32 v151, v122, v151
	v_div_scale_f32 v122, vcc, v116, v127, v116
	v_mul_f32_e32 v123, v122, v151
	v_mul_f32_e32 v120, v120, v125
	v_fma_f32 v125, -v128, v123, v122
	v_add_f32_e32 v124, 1.0, v124
	v_fmac_f32_e32 v123, v125, v151
	v_div_scale_f32 v125, s[2:3], v124, v124, v121
	v_fma_f32 v122, -v128, v123, v122
	v_rcp_f32_e32 v128, v125
	v_div_fmas_f32 v122, v122, v151, v123
	v_div_fixup_f32 v116, v122, v127, v116
	v_mul_f32_e32 v122, v116, v159
	v_fma_f32 v116, -v125, v128, 1.0
	v_mul_f32_e32 v127, 0xbfb8aa3b, v117
	v_fmac_f32_e32 v128, v116, v128
	v_div_scale_f32 v116, vcc, v121, v124, v121
	v_exp_f32_e32 v127, v127
	v_mul_f32_e32 v123, v116, v128
	v_fma_f32 v151, -v125, v123, v116
	v_fmac_f32_e32 v123, v151, v128
	v_fma_f32 v116, -v125, v123, v116
	v_add_f32_e32 v125, 1.0, v127
	v_div_scale_f32 v127, s[2:3], v125, v125, v117
	v_rcp_f32_e32 v151, v127
	v_div_fmas_f32 v116, v116, v128, v123
	v_div_fixup_f32 v116, v116, v124, v121
	v_mul_f32_e32 v121, v116, v126
	v_fma_f32 v116, -v127, v151, 1.0
	v_fmac_f32_e32 v151, v116, v151
	v_div_scale_f32 v116, vcc, v117, v125, v117
	v_mul_f32_e32 v123, v116, v151
	v_fma_f32 v124, -v127, v123, v116
	v_fmac_f32_e32 v123, v124, v151
	v_fma_f32 v116, -v127, v123, v116
	v_div_fmas_f32 v116, v116, v151, v123
	v_and_b32_e32 v129, 0xffff0000, v129
	v_div_fixup_f32 v116, v116, v125, v117
	v_mul_f32_e32 v123, v116, v129
	v_cvt_pk_bf16_f32 v116, v118, v119
	v_cvt_pk_bf16_f32 v117, v120, v121
	v_cvt_pk_bf16_f32 v118, v114, v115
	v_or_b32_e32 v114, 16, v150
	v_ashrrev_i32_e32 v115, 31, v114
	v_lshlrev_b64 v[114:115], 13, v[114:115]
	v_lshl_add_u64 v[114:115], s[10:11], 0, v[114:115]
	v_lshl_add_u64 v[114:115], v[114:115], 0, v[152:153]
	v_cvt_pk_bf16_f32 v119, v122, v123
	v_mul_f32_e32 v129, 0xbfb8aa3b, v106
	global_store_dwordx4 v[148:149], v[116:119], off offset:256
	v_exp_f32_e32 v129, v129
	s_waitcnt vmcnt(14)
	v_mov_b32_e32 v120, v194
	v_mov_b32_e32 v121, v195
	v_mov_b32_e32 v122, v196
	v_mov_b32_e32 v123, v197
	v_lshlrev_b32_e32 v126, 16, v123
	v_mul_f32_e32 v118, 0xbfb8aa3b, v110
	v_exp_f32_e32 v118, v118
	v_lshlrev_b32_e32 v116, 16, v120
	v_and_b32_e32 v117, 0xffff0000, v120
	v_lshlrev_b32_e32 v119, 16, v121
	v_add_f32_e32 v118, 1.0, v118
	v_div_scale_f32 v124, s[2:3], v118, v118, v110
	v_rcp_f32_e32 v125, v124
	v_and_b32_e32 v120, 0xffff0000, v121
	v_lshlrev_b32_e32 v121, 16, v122
	v_and_b32_e32 v122, 0xffff0000, v122
	v_fma_f32 v127, -v124, v125, 1.0
	v_fmac_f32_e32 v125, v127, v125
	v_div_scale_f32 v127, vcc, v110, v118, v110
	v_mul_f32_e32 v128, v127, v125
	v_fma_f32 v151, -v124, v128, v127
	v_fmac_f32_e32 v128, v151, v125
	v_fma_f32 v124, -v124, v128, v127
	v_add_f32_e32 v127, 1.0, v129
	v_div_scale_f32 v129, s[2:3], v127, v127, v106
	v_rcp_f32_e32 v151, v129
	v_div_fmas_f32 v124, v124, v125, v128
	v_div_fixup_f32 v110, v124, v118, v110
	v_mul_f32_e32 v124, 0xbfb8aa3b, v111
	v_exp_f32_e32 v124, v124
	v_mul_f32_e32 v110, v110, v116
	v_fma_f32 v116, -v129, v151, 1.0
	v_fmac_f32_e32 v151, v116, v151
	v_div_scale_f32 v116, vcc, v106, v127, v106
	v_mul_f32_e32 v118, v116, v151
	v_fma_f32 v125, -v129, v118, v116
	v_add_f32_e32 v124, 1.0, v124
	v_fmac_f32_e32 v118, v125, v151
	v_div_scale_f32 v125, s[2:3], v124, v124, v111
	v_fma_f32 v116, -v129, v118, v116
	v_rcp_f32_e32 v128, v125
	v_div_fmas_f32 v116, v116, v151, v118
	v_div_fixup_f32 v106, v116, v127, v106
	v_mul_f32_e32 v116, v106, v121
	v_mul_f32_e32 v121, 0xbfb8aa3b, v107
	v_fma_f32 v106, -v125, v128, 1.0
	v_exp_f32_e32 v121, v121
	v_fmac_f32_e32 v128, v106, v128
	v_div_scale_f32 v106, vcc, v111, v124, v111
	v_mul_f32_e32 v118, v106, v128
	v_fma_f32 v127, -v125, v118, v106
	v_fmac_f32_e32 v118, v127, v128
	v_add_f32_e32 v121, 1.0, v121
	v_fma_f32 v106, -v125, v118, v106
	v_div_scale_f32 v125, s[2:3], v121, v121, v107
	v_rcp_f32_e32 v127, v125
	v_div_fmas_f32 v106, v106, v128, v118
	v_mul_f32_e32 v118, 0xbfb8aa3b, v112
	v_exp_f32_e32 v118, v118
	v_div_fixup_f32 v106, v106, v124, v111
	v_fma_f32 v111, -v125, v127, 1.0
	v_fmac_f32_e32 v127, v111, v127
	v_div_scale_f32 v111, vcc, v107, v121, v107
	v_mul_f32_e32 v106, v106, v117
	v_mul_f32_e32 v117, v111, v127
	v_fma_f32 v124, -v125, v117, v111
	v_add_f32_e32 v118, 1.0, v118
	v_fmac_f32_e32 v117, v124, v127
	v_div_scale_f32 v124, s[2:3], v118, v118, v112
	v_fma_f32 v111, -v125, v117, v111
	v_rcp_f32_e32 v125, v124
	v_div_fmas_f32 v111, v111, v127, v117
	v_div_fixup_f32 v107, v111, v121, v107
	v_mul_f32_e32 v121, 0xbfb8aa3b, v108
	v_exp_f32_e32 v121, v121
	v_mul_f32_e32 v111, v107, v122
	v_fma_f32 v107, -v124, v125, 1.0
	v_fmac_f32_e32 v125, v107, v125
	v_div_scale_f32 v107, vcc, v112, v118, v112
	v_mul_f32_e32 v117, v107, v125
	v_fma_f32 v122, -v124, v117, v107
	v_add_f32_e32 v121, 1.0, v121
	v_fmac_f32_e32 v117, v122, v125
	v_div_scale_f32 v122, s[2:3], v121, v121, v108
	v_fma_f32 v107, -v124, v117, v107
	v_rcp_f32_e32 v124, v122
	v_div_fmas_f32 v107, v107, v125, v117
	v_div_fixup_f32 v107, v107, v118, v112
	v_mul_f32_e32 v118, 0xbfb8aa3b, v113
	v_exp_f32_e32 v118, v118
	v_fma_f32 v112, -v122, v124, 1.0
	v_fmac_f32_e32 v124, v112, v124
	v_div_scale_f32 v112, vcc, v108, v121, v108
	v_mul_f32_e32 v117, v112, v124
	v_mul_f32_e32 v107, v107, v119
;     __device__ __forceinline__ void operator()(const f32x4 (&acc)[2][2][4][2], const Unit& u, int wr, int wc, int fr, int fq) const {
;         const int row0 = u.pm * BM + wr * 64 + fr, col0 = u.pn * BM + wc * 32 + 8 * fq;
; #pragma unroll
;         for (int ai = 0; ai < 2; ++ai)
; #pragma unroll
;             for (int m = 0; m < 4; ++m)
; #pragma unroll
;                 for (int bj = 0; bj < 2; ++bj) f(row0 + ai * HALF + m * 16, col0 + bj * HALF, acc[ai][bj][m][0], acc[ai][bj][m][1]);
	v_fma_f32 v119, -v122, v117, v112
	v_add_f32_e32 v118, 1.0, v118
	v_fmac_f32_e32 v117, v119, v124
	v_div_scale_f32 v119, s[2:3], v118, v118, v113
	v_fma_f32 v112, -v122, v117, v112
	v_rcp_f32_e32 v122, v119
	v_div_fmas_f32 v112, v112, v124, v117
	v_div_fixup_f32 v108, v112, v121, v108
	v_mul_f32_e32 v112, v108, v126
	v_fma_f32 v108, -v119, v122, 1.0
	v_mul_f32_e32 v121, 0xbfb8aa3b, v109
	v_fmac_f32_e32 v122, v108, v122
	v_div_scale_f32 v108, vcc, v113, v118, v113
	v_exp_f32_e32 v121, v121
	v_mul_f32_e32 v117, v108, v122
	v_fma_f32 v124, -v119, v117, v108
	v_fmac_f32_e32 v117, v124, v122
	v_fma_f32 v108, -v119, v117, v108
	v_add_f32_e32 v119, 1.0, v121
	v_div_scale_f32 v121, s[2:3], v119, v119, v109
	v_rcp_f32_e32 v124, v121
	v_div_fmas_f32 v108, v108, v122, v117
	v_div_fixup_f32 v108, v108, v118, v113
	v_and_b32_e32 v123, 0xffff0000, v123
	v_fma_f32 v113, -v121, v124, 1.0
	v_fmac_f32_e32 v124, v113, v124
	v_div_scale_f32 v113, vcc, v109, v119, v109
	v_mul_f32_e32 v117, v113, v124
	v_fma_f32 v118, -v121, v117, v113
	v_fmac_f32_e32 v117, v118, v124
	v_fma_f32 v113, -v121, v117, v113
	v_div_fmas_f32 v113, v113, v124, v117
	v_div_fixup_f32 v109, v113, v119, v109
	v_mul_f32_e32 v108, v108, v120
	v_mul_f32_e32 v109, v109, v123
	v_cvt_pk_bf16_f32 v106, v110, v106
	v_cvt_pk_bf16_f32 v107, v107, v108
	v_cvt_pk_bf16_f32 v108, v116, v111
	v_cvt_pk_bf16_f32 v109, v112, v109
	v_mul_f32_e32 v121, 0xbfb8aa3b, v98
	global_store_dwordx4 v[114:115], v[106:109], off
	v_exp_f32_e32 v121, v121
	s_waitcnt vmcnt(14)
	v_mov_b32_e32 v110, v198
	v_mov_b32_e32 v111, v199
	v_mov_b32_e32 v112, v200
	v_mov_b32_e32 v113, v201
	v_lshlrev_b32_e32 v118, 16, v113
	v_mul_f32_e32 v108, 0xbfb8aa3b, v102
	v_exp_f32_e32 v108, v108
	v_lshlrev_b32_e32 v106, 16, v110
	v_and_b32_e32 v107, 0xffff0000, v110
	v_lshlrev_b32_e32 v109, 16, v111
	v_add_f32_e32 v108, 1.0, v108
	v_div_scale_f32 v116, s[2:3], v108, v108, v102
	v_rcp_f32_e32 v117, v116
	v_and_b32_e32 v110, 0xffff0000, v111
	v_lshlrev_b32_e32 v111, 16, v112
	v_and_b32_e32 v112, 0xffff0000, v112
	v_fma_f32 v119, -v116, v117, 1.0
	v_fmac_f32_e32 v117, v119, v117
	v_div_scale_f32 v119, vcc, v102, v108, v102
	v_mul_f32_e32 v120, v119, v117
	v_fma_f32 v122, -v116, v120, v119
	v_fmac_f32_e32 v120, v122, v117
	v_fma_f32 v116, -v116, v120, v119
	v_add_f32_e32 v119, 1.0, v121
	v_div_scale_f32 v121, s[2:3], v119, v119, v98
	v_rcp_f32_e32 v122, v121
	v_div_fmas_f32 v116, v116, v117, v120
	v_div_fixup_f32 v102, v116, v108, v102
	v_mul_f32_e32 v116, 0xbfb8aa3b, v103
	v_exp_f32_e32 v116, v116
	v_mul_f32_e32 v102, v102, v106
	v_fma_f32 v106, -v121, v122, 1.0
	v_fmac_f32_e32 v122, v106, v122
	v_div_scale_f32 v106, vcc, v98, v119, v98
	v_mul_f32_e32 v108, v106, v122
	v_fma_f32 v117, -v121, v108, v106
	v_add_f32_e32 v116, 1.0, v116
	v_fmac_f32_e32 v108, v117, v122
	v_div_scale_f32 v117, s[2:3], v116, v116, v103
	v_fma_f32 v106, -v121, v108, v106
	v_rcp_f32_e32 v120, v117
	v_div_fmas_f32 v106, v106, v122, v108
	v_div_fixup_f32 v98, v106, v119, v98
	v_mul_f32_e32 v98, v98, v111
	v_mul_f32_e32 v111, 0xbfb8aa3b, v99
	v_fma_f32 v106, -v117, v120, 1.0
	v_exp_f32_e32 v111, v111
	v_fmac_f32_e32 v120, v106, v120
	v_div_scale_f32 v106, vcc, v103, v116, v103
	v_mul_f32_e32 v108, v106, v120
	v_fma_f32 v119, -v117, v108, v106
	v_fmac_f32_e32 v108, v119, v120
	v_add_f32_e32 v111, 1.0, v111
	v_fma_f32 v106, -v117, v108, v106
	v_div_scale_f32 v117, s[2:3], v111, v111, v99
	v_rcp_f32_e32 v119, v117
	v_div_fmas_f32 v106, v106, v120, v108
	v_mul_f32_e32 v108, 0xbfb8aa3b, v104
	v_exp_f32_e32 v108, v108
	v_div_fixup_f32 v103, v106, v116, v103
	v_fma_f32 v106, -v117, v119, 1.0
	v_fmac_f32_e32 v119, v106, v119
	v_div_scale_f32 v106, vcc, v99, v111, v99
	v_mul_f32_e32 v103, v103, v107
	v_mul_f32_e32 v107, v106, v119
	v_fma_f32 v116, -v117, v107, v106
	v_add_f32_e32 v108, 1.0, v108
	v_fmac_f32_e32 v107, v116, v119
	v_div_scale_f32 v116, s[2:3], v108, v108, v104
	v_fma_f32 v106, -v117, v107, v106
	v_rcp_f32_e32 v117, v116
	v_div_fmas_f32 v106, v106, v119, v107
	v_div_fixup_f32 v99, v106, v111, v99
	v_mul_f32_e32 v111, 0xbfb8aa3b, v100
	v_exp_f32_e32 v111, v111
	v_fma_f32 v106, -v116, v117, 1.0
	v_fmac_f32_e32 v117, v106, v117
	v_div_scale_f32 v106, vcc, v104, v108, v104
	v_mul_f32_e32 v107, v106, v117
	v_mul_f32_e32 v99, v99, v112
	v_fma_f32 v112, -v116, v107, v106
	v_add_f32_e32 v111, 1.0, v111
	v_fmac_f32_e32 v107, v112, v117
	v_div_scale_f32 v112, s[2:3], v111, v111, v100
	v_fma_f32 v106, -v116, v107, v106
	v_rcp_f32_e32 v116, v112
	v_div_fmas_f32 v106, v106, v117, v107
	v_div_fixup_f32 v104, v106, v108, v104
	v_mul_f32_e32 v108, 0xbfb8aa3b, v105
	v_exp_f32_e32 v108, v108
	v_fma_f32 v106, -v112, v116, 1.0
	v_fmac_f32_e32 v116, v106, v116
	v_div_scale_f32 v106, vcc, v100, v111, v100
	v_mul_f32_e32 v107, v106, v116
	v_mul_f32_e32 v104, v104, v109
	v_fma_f32 v109, -v112, v107, v106
	v_add_f32_e32 v108, 1.0, v108
	v_fmac_f32_e32 v107, v109, v116
	v_div_scale_f32 v109, s[2:3], v108, v108, v105
	v_fma_f32 v106, -v112, v107, v106
	v_rcp_f32_e32 v112, v109
	v_div_fmas_f32 v106, v106, v116, v107
	v_div_fixup_f32 v100, v106, v111, v100
	v_mul_f32_e32 v106, v100, v118
	v_fma_f32 v100, -v109, v112, 1.0
	v_mul_f32_e32 v111, 0xbfb8aa3b, v101
	v_fmac_f32_e32 v112, v100, v112
	v_div_scale_f32 v100, vcc, v105, v108, v105
	v_exp_f32_e32 v111, v111
	v_mul_f32_e32 v107, v100, v112
	v_fma_f32 v116, -v109, v107, v100
	v_fmac_f32_e32 v107, v116, v112
	v_fma_f32 v100, -v109, v107, v100
	v_add_f32_e32 v109, 1.0, v111
	v_div_scale_f32 v111, s[2:3], v109, v109, v101
	v_rcp_f32_e32 v116, v111
	v_div_fmas_f32 v100, v100, v112, v107
	v_div_fixup_f32 v100, v100, v108, v105
	v_mul_f32_e32 v105, v100, v110
	v_fma_f32 v100, -v111, v116, 1.0
	v_fmac_f32_e32 v116, v100, v116
	v_div_scale_f32 v100, vcc, v101, v109, v101
	v_mul_f32_e32 v107, v100, v116
	v_fma_f32 v108, -v111, v107, v100
	v_fmac_f32_e32 v107, v108, v116
	v_fma_f32 v100, -v111, v107, v100
	v_div_fmas_f32 v100, v100, v116, v107
	v_and_b32_e32 v113, 0xffff0000, v113
	v_div_fixup_f32 v100, v100, v109, v101
	v_mul_f32_e32 v107, v100, v113
	v_cvt_pk_bf16_f32 v100, v102, v103
	v_cvt_pk_bf16_f32 v101, v104, v105
	v_cvt_pk_bf16_f32 v102, v98, v99
	v_or_b32_e32 v98, 32, v150
	v_ashrrev_i32_e32 v99, 31, v98
	v_lshlrev_b64 v[98:99], 13, v[98:99]
	v_lshl_add_u64 v[98:99], s[10:11], 0, v[98:99]
	v_lshl_add_u64 v[98:99], v[98:99], 0, v[152:153]
	v_cvt_pk_bf16_f32 v103, v106, v107
	v_mul_f32_e32 v113, 0xbfb8aa3b, v90
	global_store_dwordx4 v[114:115], v[100:103], off offset:256
	v_exp_f32_e32 v113, v113
	s_waitcnt vmcnt(14)
;     __device__ __forceinline__ void operator()(const f32x4 (&acc)[2][2][4][2], const Unit& u, int wr, int wc, int fr, int fq) const {
;         const int row0 = u.pm * BM + wr * 64 + fr, col0 = u.pn * BM + wc * 32 + 8 * fq;
; #pragma unroll
;         for (int ai = 0; ai < 2; ++ai)
; #pragma unroll
;             for (int m = 0; m < 4; ++m)
; #pragma unroll
;                 for (int bj = 0; bj < 2; ++bj) f(row0 + ai * HALF + m * 16, col0 + bj * HALF, acc[ai][bj][m][0], acc[ai][bj][m][1]);
	v_mov_b32_e32 v104, v202
	v_mov_b32_e32 v105, v203
	v_mov_b32_e32 v106, v204
	v_mov_b32_e32 v107, v205
	v_lshlrev_b32_e32 v110, 16, v107
	v_mul_f32_e32 v102, 0xbfb8aa3b, v94
	v_exp_f32_e32 v102, v102
	v_lshlrev_b32_e32 v100, 16, v104
	v_and_b32_e32 v101, 0xffff0000, v104
	v_lshlrev_b32_e32 v103, 16, v105
	v_add_f32_e32 v102, 1.0, v102
	v_div_scale_f32 v108, s[2:3], v102, v102, v94
	v_rcp_f32_e32 v109, v108
	v_and_b32_e32 v104, 0xffff0000, v105
	v_lshlrev_b32_e32 v105, 16, v106
	v_and_b32_e32 v106, 0xffff0000, v106
	v_fma_f32 v111, -v108, v109, 1.0
	v_fmac_f32_e32 v109, v111, v109
	v_div_scale_f32 v111, vcc, v94, v102, v94
	v_mul_f32_e32 v112, v111, v109
	v_fma_f32 v114, -v108, v112, v111
	v_fmac_f32_e32 v112, v114, v109
	v_fma_f32 v108, -v108, v112, v111
	v_add_f32_e32 v111, 1.0, v113
	v_div_scale_f32 v113, s[2:3], v111, v111, v90
	v_rcp_f32_e32 v114, v113
	v_div_fmas_f32 v108, v108, v109, v112
	v_div_fixup_f32 v94, v108, v102, v94
	v_mul_f32_e32 v108, 0xbfb8aa3b, v95
	v_exp_f32_e32 v108, v108
	v_mul_f32_e32 v94, v94, v100
	v_fma_f32 v100, -v113, v114, 1.0
	v_fmac_f32_e32 v114, v100, v114
	v_div_scale_f32 v100, vcc, v90, v111, v90
	v_mul_f32_e32 v102, v100, v114
	v_fma_f32 v109, -v113, v102, v100
	v_add_f32_e32 v108, 1.0, v108
	v_fmac_f32_e32 v102, v109, v114
	v_div_scale_f32 v109, s[2:3], v108, v108, v95
	v_fma_f32 v100, -v113, v102, v100
	v_rcp_f32_e32 v112, v109
	v_div_fmas_f32 v100, v100, v114, v102
	v_div_fixup_f32 v90, v100, v111, v90
	v_mul_f32_e32 v100, v90, v105
	v_mul_f32_e32 v105, 0xbfb8aa3b, v91
	v_fma_f32 v90, -v109, v112, 1.0
	v_exp_f32_e32 v105, v105
	v_fmac_f32_e32 v112, v90, v112
	v_div_scale_f32 v90, vcc, v95, v108, v95
	v_mul_f32_e32 v102, v90, v112
	v_fma_f32 v111, -v109, v102, v90
	v_fmac_f32_e32 v102, v111, v112
	v_add_f32_e32 v105, 1.0, v105
	v_fma_f32 v90, -v109, v102, v90
	v_div_scale_f32 v109, s[2:3], v105, v105, v91
	v_rcp_f32_e32 v111, v109
	v_div_fmas_f32 v90, v90, v112, v102
	v_mul_f32_e32 v102, 0xbfb8aa3b, v96
	v_exp_f32_e32 v102, v102
	v_div_fixup_f32 v90, v90, v108, v95
	v_fma_f32 v95, -v109, v111, 1.0
	v_fmac_f32_e32 v111, v95, v111
	v_div_scale_f32 v95, vcc, v91, v105, v91
	v_mul_f32_e32 v90, v90, v101
	v_mul_f32_e32 v101, v95, v111
	v_fma_f32 v108, -v109, v101, v95
	v_add_f32_e32 v102, 1.0, v102
	v_fmac_f32_e32 v101, v108, v111
	v_div_scale_f32 v108, s[2:3], v102, v102, v96
	v_fma_f32 v95, -v109, v101, v95
	v_rcp_f32_e32 v109, v108
	v_div_fmas_f32 v95, v95, v111, v101
	v_div_fixup_f32 v91, v95, v105, v91
	v_mul_f32_e32 v105, 0xbfb8aa3b, v92
	v_exp_f32_e32 v105, v105
	v_mul_f32_e32 v95, v91, v106
	v_fma_f32 v91, -v108, v109, 1.0
	v_fmac_f32_e32 v109, v91, v109
	v_div_scale_f32 v91, vcc, v96, v102, v96
	v_mul_f32_e32 v101, v91, v109
	v_fma_f32 v106, -v108, v101, v91
	v_add_f32_e32 v105, 1.0, v105
	v_fmac_f32_e32 v101, v106, v109
	v_div_scale_f32 v106, s[2:3], v105, v105, v92
	v_fma_f32 v91, -v108, v101, v91
	v_rcp_f32_e32 v108, v106
	v_div_fmas_f32 v91, v91, v109, v101
	v_div_fixup_f32 v91, v91, v102, v96
	v_mul_f32_e32 v102, 0xbfb8aa3b, v97
	v_exp_f32_e32 v102, v102
	v_fma_f32 v96, -v106, v108, 1.0
	v_fmac_f32_e32 v108, v96, v108
	v_div_scale_f32 v96, vcc, v92, v105, v92
	v_mul_f32_e32 v101, v96, v108
	v_mul_f32_e32 v91, v91, v103
	v_fma_f32 v103, -v106, v101, v96
	v_add_f32_e32 v102, 1.0, v102
	v_fmac_f32_e32 v101, v103, v108
	v_div_scale_f32 v103, s[2:3], v102, v102, v97
	v_fma_f32 v96, -v106, v101, v96
	v_rcp_f32_e32 v106, v103
	v_div_fmas_f32 v96, v96, v108, v101
	v_div_fixup_f32 v92, v96, v105, v92
	v_mul_f32_e32 v96, v92, v110
	v_fma_f32 v92, -v103, v106, 1.0
	v_mul_f32_e32 v105, 0xbfb8aa3b, v93
	v_fmac_f32_e32 v106, v92, v106
	v_div_scale_f32 v92, vcc, v97, v102, v97
	v_exp_f32_e32 v105, v105
	v_mul_f32_e32 v101, v92, v106
	v_fma_f32 v108, -v103, v101, v92
	v_fmac_f32_e32 v101, v108, v106
	v_fma_f32 v92, -v103, v101, v92
	v_add_f32_e32 v103, 1.0, v105
	v_div_scale_f32 v105, s[2:3], v103, v103, v93
	v_rcp_f32_e32 v108, v105
	v_div_fmas_f32 v92, v92, v106, v101
	v_div_fixup_f32 v92, v92, v102, v97
	v_and_b32_e32 v107, 0xffff0000, v107
	v_fma_f32 v97, -v105, v108, 1.0
	v_fmac_f32_e32 v108, v97, v108
	v_div_scale_f32 v97, vcc, v93, v103, v93
	v_mul_f32_e32 v101, v97, v108
	v_fma_f32 v102, -v105, v101, v97
	v_fmac_f32_e32 v101, v102, v108
	v_fma_f32 v97, -v105, v101, v97
	v_div_fmas_f32 v97, v97, v108, v101
	v_div_fixup_f32 v93, v97, v103, v93
	v_mul_f32_e32 v92, v92, v104
	v_mul_f32_e32 v93, v93, v107
	v_cvt_pk_bf16_f32 v90, v94, v90
	v_cvt_pk_bf16_f32 v91, v91, v92
	v_cvt_pk_bf16_f32 v92, v100, v95
	v_cvt_pk_bf16_f32 v93, v96, v93
	v_mul_f32_e32 v105, 0xbfb8aa3b, v82
	global_store_dwordx4 v[98:99], v[90:93], off
	v_exp_f32_e32 v105, v105
	s_waitcnt vmcnt(14)
;     __device__ __forceinline__ void operator()(const f32x4 (&acc)[2][2][4][2], const Unit& u, int wr, int wc, int fr, int fq) const {
;         const int row0 = u.pm * BM + wr * 64 + fr, col0 = u.pn * BM + wc * 32 + 8 * fq;
; #pragma unroll
;         for (int ai = 0; ai < 2; ++ai)
; #pragma unroll
;             for (int m = 0; m < 4; ++m)
; #pragma unroll
;                 for (int bj = 0; bj < 2; ++bj) f(row0 + ai * HALF + m * 16, col0 + bj * HALF, acc[ai][bj][m][0], acc[ai][bj][m][1]);
	v_mov_b32_e32 v94, v206
	v_mov_b32_e32 v95, v207
	v_mov_b32_e32 v96, v208
	v_mov_b32_e32 v97, v209
	v_lshlrev_b32_e32 v102, 16, v97
	v_mul_f32_e32 v92, 0xbfb8aa3b, v86
	v_exp_f32_e32 v92, v92
	v_lshlrev_b32_e32 v90, 16, v94
	v_and_b32_e32 v91, 0xffff0000, v94
	v_lshlrev_b32_e32 v93, 16, v95
	v_add_f32_e32 v92, 1.0, v92
	v_div_scale_f32 v100, s[2:3], v92, v92, v86
	v_rcp_f32_e32 v101, v100
	v_and_b32_e32 v94, 0xffff0000, v95
	v_lshlrev_b32_e32 v95, 16, v96
	v_and_b32_e32 v96, 0xffff0000, v96
	v_fma_f32 v103, -v100, v101, 1.0
	v_fmac_f32_e32 v101, v103, v101
	v_div_scale_f32 v103, vcc, v86, v92, v86
	v_mul_f32_e32 v104, v103, v101
	v_fma_f32 v106, -v100, v104, v103
	v_fmac_f32_e32 v104, v106, v101
	v_fma_f32 v100, -v100, v104, v103
	v_add_f32_e32 v103, 1.0, v105
	v_div_scale_f32 v105, s[2:3], v103, v103, v82
	v_rcp_f32_e32 v106, v105
	v_div_fmas_f32 v100, v100, v101, v104
	v_div_fixup_f32 v86, v100, v92, v86
	v_mul_f32_e32 v100, 0xbfb8aa3b, v87
	v_exp_f32_e32 v100, v100
	v_mul_f32_e32 v86, v86, v90
	v_fma_f32 v90, -v105, v106, 1.0
	v_fmac_f32_e32 v106, v90, v106
	v_div_scale_f32 v90, vcc, v82, v103, v82
	v_mul_f32_e32 v92, v90, v106
	v_fma_f32 v101, -v105, v92, v90
	v_add_f32_e32 v100, 1.0, v100
	v_fmac_f32_e32 v92, v101, v106
	v_div_scale_f32 v101, s[2:3], v100, v100, v87
	v_fma_f32 v90, -v105, v92, v90
	v_rcp_f32_e32 v104, v101
	v_div_fmas_f32 v90, v90, v106, v92
	v_div_fixup_f32 v82, v90, v103, v82
	v_mul_f32_e32 v82, v82, v95
	v_mul_f32_e32 v95, 0xbfb8aa3b, v83
	v_fma_f32 v90, -v101, v104, 1.0
	v_exp_f32_e32 v95, v95
	v_fmac_f32_e32 v104, v90, v104
	v_div_scale_f32 v90, vcc, v87, v100, v87
	v_mul_f32_e32 v92, v90, v104
	v_fma_f32 v103, -v101, v92, v90
	v_fmac_f32_e32 v92, v103, v104
	v_add_f32_e32 v95, 1.0, v95
	v_fma_f32 v90, -v101, v92, v90
	v_div_scale_f32 v101, s[2:3], v95, v95, v83
	v_rcp_f32_e32 v103, v101
	v_div_fmas_f32 v90, v90, v104, v92
	v_mul_f32_e32 v92, 0xbfb8aa3b, v88
	v_exp_f32_e32 v92, v92
	v_div_fixup_f32 v87, v90, v100, v87
	v_fma_f32 v90, -v101, v103, 1.0
	v_fmac_f32_e32 v103, v90, v103
	v_div_scale_f32 v90, vcc, v83, v95, v83
	v_mul_f32_e32 v87, v87, v91
	v_mul_f32_e32 v91, v90, v103
	v_fma_f32 v100, -v101, v91, v90
	v_add_f32_e32 v92, 1.0, v92
	v_fmac_f32_e32 v91, v100, v103
	v_div_scale_f32 v100, s[2:3], v92, v92, v88
	v_fma_f32 v90, -v101, v91, v90
	v_rcp_f32_e32 v101, v100
	v_div_fmas_f32 v90, v90, v103, v91
	v_div_fixup_f32 v83, v90, v95, v83
	v_mul_f32_e32 v95, 0xbfb8aa3b, v84
	v_exp_f32_e32 v95, v95
	v_fma_f32 v90, -v100, v101, 1.0
	v_fmac_f32_e32 v101, v90, v101
	v_div_scale_f32 v90, vcc, v88, v92, v88
	v_mul_f32_e32 v91, v90, v101
	v_mul_f32_e32 v83, v83, v96
	v_fma_f32 v96, -v100, v91, v90
	v_add_f32_e32 v95, 1.0, v95
	v_fmac_f32_e32 v91, v96, v101
	v_div_scale_f32 v96, s[2:3], v95, v95, v84
	v_fma_f32 v90, -v100, v91, v90
	v_rcp_f32_e32 v100, v96
	v_div_fmas_f32 v90, v90, v101, v91
	v_div_fixup_f32 v88, v90, v92, v88
	v_mul_f32_e32 v92, 0xbfb8aa3b, v89
	v_exp_f32_e32 v92, v92
	v_fma_f32 v90, -v96, v100, 1.0
	v_fmac_f32_e32 v100, v90, v100
	v_div_scale_f32 v90, vcc, v84, v95, v84
	v_mul_f32_e32 v91, v90, v100
	v_mul_f32_e32 v88, v88, v93
	v_fma_f32 v93, -v96, v91, v90
	v_add_f32_e32 v92, 1.0, v92
	v_fmac_f32_e32 v91, v93, v100
	v_div_scale_f32 v93, s[2:3], v92, v92, v89
	v_fma_f32 v90, -v96, v91, v90
	v_rcp_f32_e32 v96, v93
	v_div_fmas_f32 v90, v90, v100, v91
	v_div_fixup_f32 v84, v90, v95, v84
	v_mul_f32_e32 v90, v84, v102
	v_fma_f32 v84, -v93, v96, 1.0
	v_mul_f32_e32 v95, 0xbfb8aa3b, v85
	v_fmac_f32_e32 v96, v84, v96
	v_div_scale_f32 v84, vcc, v89, v92, v89
	v_exp_f32_e32 v95, v95
	v_mul_f32_e32 v91, v84, v96
	v_fma_f32 v100, -v93, v91, v84
	v_fmac_f32_e32 v91, v100, v96
	v_fma_f32 v84, -v93, v91, v84
	v_add_f32_e32 v93, 1.0, v95
	v_div_scale_f32 v95, s[2:3], v93, v93, v85
	v_rcp_f32_e32 v100, v95
	v_div_fmas_f32 v84, v84, v96, v91
	v_div_fixup_f32 v84, v84, v92, v89
	v_mul_f32_e32 v89, v84, v94
	v_fma_f32 v84, -v95, v100, 1.0
	v_fmac_f32_e32 v100, v84, v100
	v_div_scale_f32 v84, vcc, v85, v93, v85
	v_mul_f32_e32 v91, v84, v100
	v_fma_f32 v92, -v95, v91, v84
	v_fmac_f32_e32 v91, v92, v100
	v_fma_f32 v84, -v95, v91, v84
	v_div_fmas_f32 v84, v84, v100, v91
	v_and_b32_e32 v97, 0xffff0000, v97
	v_div_fixup_f32 v84, v84, v93, v85
	v_mul_f32_e32 v91, v84, v97
	v_cvt_pk_bf16_f32 v84, v86, v87
	v_cvt_pk_bf16_f32 v85, v88, v89
	v_cvt_pk_bf16_f32 v86, v82, v83
	v_or_b32_e32 v82, 48, v150
	v_ashrrev_i32_e32 v83, 31, v82
	v_lshlrev_b64 v[82:83], 13, v[82:83]
	v_lshl_add_u64 v[82:83], s[10:11], 0, v[82:83]
	v_lshl_add_u64 v[82:83], v[82:83], 0, v[152:153]
	v_cvt_pk_bf16_f32 v87, v90, v91
	v_mul_f32_e32 v97, 0xbfb8aa3b, v74
	global_store_dwordx4 v[98:99], v[84:87], off offset:256
	v_exp_f32_e32 v97, v97
	s_waitcnt vmcnt(14)
;     __device__ __forceinline__ void operator()(const f32x4 (&acc)[2][2][4][2], const Unit& u, int wr, int wc, int fr, int fq) const {
;         const int row0 = u.pm * BM + wr * 64 + fr, col0 = u.pn * BM + wc * 32 + 8 * fq;
; #pragma unroll
;         for (int ai = 0; ai < 2; ++ai)
; #pragma unroll
;             for (int m = 0; m < 4; ++m)
; #pragma unroll
;                 for (int bj = 0; bj < 2; ++bj) f(row0 + ai * HALF + m * 16, col0 + bj * HALF, acc[ai][bj][m][0], acc[ai][bj][m][1]);
	v_mov_b32_e32 v88, v210
	v_mov_b32_e32 v89, v211
	v_mov_b32_e32 v90, v212
	v_mov_b32_e32 v91, v213
	v_lshlrev_b32_e32 v94, 16, v91
	v_mul_f32_e32 v86, 0xbfb8aa3b, v78
	v_exp_f32_e32 v86, v86
	v_lshlrev_b32_e32 v84, 16, v88
	v_and_b32_e32 v85, 0xffff0000, v88
	v_lshlrev_b32_e32 v87, 16, v89
	v_add_f32_e32 v86, 1.0, v86
	v_div_scale_f32 v92, s[2:3], v86, v86, v78
	v_rcp_f32_e32 v93, v92
	v_and_b32_e32 v88, 0xffff0000, v89
	v_lshlrev_b32_e32 v89, 16, v90
	v_and_b32_e32 v90, 0xffff0000, v90
	v_fma_f32 v95, -v92, v93, 1.0
	v_fmac_f32_e32 v93, v95, v93
	v_div_scale_f32 v95, vcc, v78, v86, v78
	v_mul_f32_e32 v96, v95, v93
	v_fma_f32 v98, -v92, v96, v95
	v_fmac_f32_e32 v96, v98, v93
	v_fma_f32 v92, -v92, v96, v95
	v_add_f32_e32 v95, 1.0, v97
	v_div_scale_f32 v97, s[2:3], v95, v95, v74
	v_rcp_f32_e32 v98, v97
	v_div_fmas_f32 v92, v92, v93, v96
	v_div_fixup_f32 v78, v92, v86, v78
	v_mul_f32_e32 v92, 0xbfb8aa3b, v79
	v_exp_f32_e32 v92, v92
	v_mul_f32_e32 v78, v78, v84
	v_fma_f32 v84, -v97, v98, 1.0
	v_fmac_f32_e32 v98, v84, v98
	v_div_scale_f32 v84, vcc, v74, v95, v74
	v_mul_f32_e32 v86, v84, v98
	v_fma_f32 v93, -v97, v86, v84
	v_add_f32_e32 v92, 1.0, v92
	v_fmac_f32_e32 v86, v93, v98
	v_div_scale_f32 v93, s[2:3], v92, v92, v79
	v_fma_f32 v84, -v97, v86, v84
	v_rcp_f32_e32 v96, v93
	v_div_fmas_f32 v84, v84, v98, v86
	v_div_fixup_f32 v74, v84, v95, v74
	v_mul_f32_e32 v84, v74, v89
	v_mul_f32_e32 v89, 0xbfb8aa3b, v75
	v_fma_f32 v74, -v93, v96, 1.0
	v_exp_f32_e32 v89, v89
	v_fmac_f32_e32 v96, v74, v96
	v_div_scale_f32 v74, vcc, v79, v92, v79
	v_mul_f32_e32 v86, v74, v96
	v_fma_f32 v95, -v93, v86, v74
	v_fmac_f32_e32 v86, v95, v96
	v_add_f32_e32 v89, 1.0, v89
	v_fma_f32 v74, -v93, v86, v74
	v_div_scale_f32 v93, s[2:3], v89, v89, v75
	v_rcp_f32_e32 v95, v93
	v_div_fmas_f32 v74, v74, v96, v86
	v_mul_f32_e32 v86, 0xbfb8aa3b, v80
	v_exp_f32_e32 v86, v86
	v_div_fixup_f32 v74, v74, v92, v79
	v_fma_f32 v79, -v93, v95, 1.0
	v_fmac_f32_e32 v95, v79, v95
	v_div_scale_f32 v79, vcc, v75, v89, v75
	v_mul_f32_e32 v74, v74, v85
	v_mul_f32_e32 v85, v79, v95
	v_fma_f32 v92, -v93, v85, v79
	v_add_f32_e32 v86, 1.0, v86
	v_fmac_f32_e32 v85, v92, v95
	v_div_scale_f32 v92, s[2:3], v86, v86, v80
	v_fma_f32 v79, -v93, v85, v79
	v_rcp_f32_e32 v93, v92
	v_div_fmas_f32 v79, v79, v95, v85
	v_div_fixup_f32 v75, v79, v89, v75
	v_mul_f32_e32 v89, 0xbfb8aa3b, v76
	v_exp_f32_e32 v89, v89
	v_mul_f32_e32 v79, v75, v90
	v_fma_f32 v75, -v92, v93, 1.0
	v_fmac_f32_e32 v93, v75, v93
	v_div_scale_f32 v75, vcc, v80, v86, v80
	v_mul_f32_e32 v85, v75, v93
	v_fma_f32 v90, -v92, v85, v75
	v_add_f32_e32 v89, 1.0, v89
	v_fmac_f32_e32 v85, v90, v93
	v_div_scale_f32 v90, s[2:3], v89, v89, v76
	v_fma_f32 v75, -v92, v85, v75
	v_rcp_f32_e32 v92, v90
	v_div_fmas_f32 v75, v75, v93, v85
	v_div_fixup_f32 v75, v75, v86, v80
	v_mul_f32_e32 v86, 0xbfb8aa3b, v81
	v_exp_f32_e32 v86, v86
	v_fma_f32 v80, -v90, v92, 1.0
	v_fmac_f32_e32 v92, v80, v92
	v_div_scale_f32 v80, vcc, v76, v89, v76
	v_mul_f32_e32 v85, v80, v92
	v_mul_f32_e32 v75, v75, v87
	v_fma_f32 v87, -v90, v85, v80
	v_add_f32_e32 v86, 1.0, v86
	v_fmac_f32_e32 v85, v87, v92
	v_div_scale_f32 v87, s[2:3], v86, v86, v81
	v_fma_f32 v80, -v90, v85, v80
	v_rcp_f32_e32 v90, v87
	v_div_fmas_f32 v80, v80, v92, v85
	v_div_fixup_f32 v76, v80, v89, v76
	v_mul_f32_e32 v80, v76, v94
	v_fma_f32 v76, -v87, v90, 1.0
	v_mul_f32_e32 v89, 0xbfb8aa3b, v77
	v_fmac_f32_e32 v90, v76, v90
	v_div_scale_f32 v76, vcc, v81, v86, v81
	v_exp_f32_e32 v89, v89
	v_mul_f32_e32 v85, v76, v90
	v_fma_f32 v92, -v87, v85, v76
	v_fmac_f32_e32 v85, v92, v90
	v_fma_f32 v76, -v87, v85, v76
	v_add_f32_e32 v87, 1.0, v89
	v_div_scale_f32 v89, s[2:3], v87, v87, v77
	v_rcp_f32_e32 v92, v89
	v_div_fmas_f32 v76, v76, v90, v85
	v_div_fixup_f32 v76, v76, v86, v81
	v_and_b32_e32 v91, 0xffff0000, v91
	v_fma_f32 v81, -v89, v92, 1.0
	v_fmac_f32_e32 v92, v81, v92
	v_div_scale_f32 v81, vcc, v77, v87, v77
	v_mul_f32_e32 v85, v81, v92
	v_fma_f32 v86, -v89, v85, v81
	v_fmac_f32_e32 v85, v86, v92
	v_fma_f32 v81, -v89, v85, v81
	v_div_fmas_f32 v81, v81, v92, v85
	v_div_fixup_f32 v77, v81, v87, v77
	v_mul_f32_e32 v76, v76, v88
	v_mul_f32_e32 v77, v77, v91
	v_cvt_pk_bf16_f32 v74, v78, v74
	v_cvt_pk_bf16_f32 v75, v75, v76
	v_cvt_pk_bf16_f32 v76, v84, v79
	v_cvt_pk_bf16_f32 v77, v80, v77
	v_mul_f32_e32 v89, 0xbfb8aa3b, v66
	global_store_dwordx4 v[82:83], v[74:77], off
	v_exp_f32_e32 v89, v89
	s_waitcnt vmcnt(14)
;     __device__ __forceinline__ void operator()(const f32x4 (&acc)[2][2][4][2], const Unit& u, int wr, int wc, int fr, int fq) const {
;         const int row0 = u.pm * BM + wr * 64 + fr, col0 = u.pn * BM + wc * 32 + 8 * fq;
; #pragma unroll
;         for (int ai = 0; ai < 2; ++ai)
; #pragma unroll
;             for (int m = 0; m < 4; ++m)
; #pragma unroll
;                 for (int bj = 0; bj < 2; ++bj) f(row0 + ai * HALF + m * 16, col0 + bj * HALF, acc[ai][bj][m][0], acc[ai][bj][m][1]);
	v_mov_b32_e32 v78, v214
	v_mov_b32_e32 v79, v215
	v_mov_b32_e32 v80, v216
	v_mov_b32_e32 v81, v217
	v_lshlrev_b32_e32 v86, 16, v81
	v_mul_f32_e32 v76, 0xbfb8aa3b, v70
	v_exp_f32_e32 v76, v76
	v_lshlrev_b32_e32 v74, 16, v78
	v_and_b32_e32 v75, 0xffff0000, v78
	v_lshlrev_b32_e32 v77, 16, v79
	v_add_f32_e32 v76, 1.0, v76
	v_div_scale_f32 v84, s[2:3], v76, v76, v70
	v_rcp_f32_e32 v85, v84
	v_and_b32_e32 v78, 0xffff0000, v79
	v_lshlrev_b32_e32 v79, 16, v80
	v_and_b32_e32 v80, 0xffff0000, v80
	v_fma_f32 v87, -v84, v85, 1.0
	v_fmac_f32_e32 v85, v87, v85
	v_div_scale_f32 v87, vcc, v70, v76, v70
	v_mul_f32_e32 v88, v87, v85
	v_fma_f32 v90, -v84, v88, v87
	v_fmac_f32_e32 v88, v90, v85
	v_fma_f32 v84, -v84, v88, v87
	v_add_f32_e32 v87, 1.0, v89
	v_div_scale_f32 v89, s[2:3], v87, v87, v66
	v_rcp_f32_e32 v90, v89
	v_div_fmas_f32 v84, v84, v85, v88
	v_div_fixup_f32 v70, v84, v76, v70
	v_mul_f32_e32 v84, 0xbfb8aa3b, v71
	v_exp_f32_e32 v84, v84
	v_mul_f32_e32 v70, v70, v74
	v_fma_f32 v74, -v89, v90, 1.0
	v_fmac_f32_e32 v90, v74, v90
	v_div_scale_f32 v74, vcc, v66, v87, v66
	v_mul_f32_e32 v76, v74, v90
	v_fma_f32 v85, -v89, v76, v74
	v_add_f32_e32 v84, 1.0, v84
	v_fmac_f32_e32 v76, v85, v90
	v_div_scale_f32 v85, s[2:3], v84, v84, v71
	v_fma_f32 v74, -v89, v76, v74
	v_rcp_f32_e32 v88, v85
	v_div_fmas_f32 v74, v74, v90, v76
	v_div_fixup_f32 v66, v74, v87, v66
	v_mul_f32_e32 v74, v66, v79
	v_mul_f32_e32 v79, 0xbfb8aa3b, v67
	v_fma_f32 v66, -v85, v88, 1.0
	v_exp_f32_e32 v79, v79
	v_fmac_f32_e32 v88, v66, v88
	v_div_scale_f32 v66, vcc, v71, v84, v71
	v_mul_f32_e32 v76, v66, v88
	v_fma_f32 v87, -v85, v76, v66
	v_fmac_f32_e32 v76, v87, v88
	v_add_f32_e32 v79, 1.0, v79
	v_fma_f32 v66, -v85, v76, v66
	v_div_scale_f32 v85, s[2:3], v79, v79, v67
	v_rcp_f32_e32 v87, v85
	v_div_fmas_f32 v66, v66, v88, v76
	v_mul_f32_e32 v76, 0xbfb8aa3b, v72
	v_exp_f32_e32 v76, v76
	v_div_fixup_f32 v66, v66, v84, v71
	v_fma_f32 v71, -v85, v87, 1.0
	v_fmac_f32_e32 v87, v71, v87
	v_div_scale_f32 v71, vcc, v67, v79, v67
	v_mul_f32_e32 v66, v66, v75
	v_mul_f32_e32 v75, v71, v87
	v_fma_f32 v84, -v85, v75, v71
	v_add_f32_e32 v76, 1.0, v76
	v_fmac_f32_e32 v75, v84, v87
	v_div_scale_f32 v84, s[2:3], v76, v76, v72
	v_fma_f32 v71, -v85, v75, v71
	v_rcp_f32_e32 v85, v84
	v_div_fmas_f32 v71, v71, v87, v75
	v_div_fixup_f32 v67, v71, v79, v67
	v_mul_f32_e32 v79, 0xbfb8aa3b, v68
	v_exp_f32_e32 v79, v79
	v_mul_f32_e32 v71, v67, v80
	v_fma_f32 v67, -v84, v85, 1.0
	v_fmac_f32_e32 v85, v67, v85
	v_div_scale_f32 v67, vcc, v72, v76, v72
	v_mul_f32_e32 v75, v67, v85
	v_fma_f32 v80, -v84, v75, v67
	v_add_f32_e32 v79, 1.0, v79
	v_fmac_f32_e32 v75, v80, v85
	v_div_scale_f32 v80, s[2:3], v79, v79, v68
	v_fma_f32 v67, -v84, v75, v67
	v_rcp_f32_e32 v84, v80
	v_div_fmas_f32 v67, v67, v85, v75
	v_div_fixup_f32 v67, v67, v76, v72
	v_mul_f32_e32 v76, 0xbfb8aa3b, v73
	v_exp_f32_e32 v76, v76
	v_fma_f32 v72, -v80, v84, 1.0
	v_fmac_f32_e32 v84, v72, v84
	v_div_scale_f32 v72, vcc, v68, v79, v68
	v_mul_f32_e32 v75, v72, v84
	v_mul_f32_e32 v67, v67, v77
	v_fma_f32 v77, -v80, v75, v72
	v_add_f32_e32 v76, 1.0, v76
	v_fmac_f32_e32 v75, v77, v84
	v_div_scale_f32 v77, s[2:3], v76, v76, v73
	v_fma_f32 v72, -v80, v75, v72
	v_rcp_f32_e32 v80, v77
	v_div_fmas_f32 v72, v72, v84, v75
	v_div_fixup_f32 v68, v72, v79, v68
	v_mul_f32_e32 v72, v68, v86
	v_fma_f32 v68, -v77, v80, 1.0
	v_mul_f32_e32 v79, 0xbfb8aa3b, v69
	v_fmac_f32_e32 v80, v68, v80
	v_div_scale_f32 v68, vcc, v73, v76, v73
	v_exp_f32_e32 v79, v79
	v_mul_f32_e32 v75, v68, v80
	v_fma_f32 v84, -v77, v75, v68
	v_fmac_f32_e32 v75, v84, v80
	v_fma_f32 v68, -v77, v75, v68
	v_add_f32_e32 v77, 1.0, v79
	v_div_scale_f32 v79, s[2:3], v77, v77, v69
	v_rcp_f32_e32 v84, v79
	v_div_fmas_f32 v68, v68, v80, v75
	v_div_fixup_f32 v68, v68, v76, v73
	v_mul_f32_e32 v68, v68, v78
	v_fma_f32 v73, -v79, v84, 1.0
	v_fmac_f32_e32 v84, v73, v84
	v_div_scale_f32 v73, vcc, v69, v77, v69
	v_mul_f32_e32 v75, v73, v84
	v_fma_f32 v76, -v79, v75, v73
	v_fmac_f32_e32 v75, v76, v84
	v_fma_f32 v73, -v79, v75, v73
	v_div_fmas_f32 v73, v73, v84, v75
	v_and_b32_e32 v81, 0xffff0000, v81
	v_div_fixup_f32 v69, v73, v77, v69
	v_cvt_pk_bf16_f32 v66, v70, v66
	v_cvt_pk_bf16_f32 v67, v67, v68
	v_cvt_pk_bf16_f32 v68, v74, v71
	v_add_co_u32_e32 v74, vcc, s48, v148
	v_mul_f32_e32 v69, v69, v81
	s_nop 0
	v_addc_co_u32_e32 v75, vcc, 0, v149, vcc
	v_cvt_pk_bf16_f32 v69, v72, v69
	s_waitcnt vmcnt(14)
;     __device__ __forceinline__ void operator()(const f32x4 (&acc)[2][2][4][2], const Unit& u, int wr, int wc, int fr, int fq) const {
;         const int row0 = u.pm * BM + wr * 64 + fr, col0 = u.pn * BM + wc * 32 + 8 * fq;
; #pragma unroll
;         for (int ai = 0; ai < 2; ++ai)
; #pragma unroll
;             for (int m = 0; m < 4; ++m)
; #pragma unroll
;                 for (int bj = 0; bj < 2; ++bj) f(row0 + ai * HALF + m * 16, col0 + bj * HALF, acc[ai][bj][m][0], acc[ai][bj][m][1]);
	v_mov_b32_e32 v70, v218
	v_mov_b32_e32 v71, v219
	v_mov_b32_e32 v72, v220
	v_mov_b32_e32 v73, v221
	v_lshlrev_b32_e32 v77, 16, v72
	global_store_dwordx4 v[82:83], v[66:69], off offset:256
	v_mul_f32_e32 v83, 0xbfb8aa3b, v58
	v_exp_f32_e32 v83, v83
	v_lshlrev_b32_e32 v68, 16, v70
	v_and_b32_e32 v69, 0xffff0000, v70
	v_mul_f32_e32 v70, 0xbfb8aa3b, v62
	v_exp_f32_e32 v70, v70
	v_and_b32_e32 v72, 0xffff0000, v72
	v_lshlrev_b32_e32 v76, 16, v71
	v_lshlrev_b32_e32 v80, 16, v73
	v_add_f32_e32 v70, 1.0, v70
	v_div_scale_f32 v78, s[2:3], v70, v70, v62
	v_rcp_f32_e32 v79, v78
	v_and_b32_e32 v71, 0xffff0000, v71
	v_and_b32_e32 v73, 0xffff0000, v73
	v_lshl_add_u64 v[66:67], v[148:149], 0, s[14:15]
	v_fma_f32 v81, -v78, v79, 1.0
	v_fmac_f32_e32 v79, v81, v79
	v_div_scale_f32 v81, vcc, v62, v70, v62
	v_mul_f32_e32 v82, v81, v79
	v_fma_f32 v84, -v78, v82, v81
	v_fmac_f32_e32 v82, v84, v79
	v_fma_f32 v78, -v78, v82, v81
	v_add_f32_e32 v81, 1.0, v83
	v_div_scale_f32 v83, s[2:3], v81, v81, v58
	v_rcp_f32_e32 v84, v83
	v_div_fmas_f32 v78, v78, v79, v82
	v_div_fixup_f32 v62, v78, v70, v62
	v_mul_f32_e32 v78, 0xbfb8aa3b, v63
	v_exp_f32_e32 v78, v78
	v_mul_f32_e32 v62, v62, v68
	v_fma_f32 v68, -v83, v84, 1.0
	v_fmac_f32_e32 v84, v68, v84
	v_div_scale_f32 v68, vcc, v58, v81, v58
	v_mul_f32_e32 v70, v68, v84
	v_fma_f32 v79, -v83, v70, v68
	v_add_f32_e32 v78, 1.0, v78
	v_fmac_f32_e32 v70, v79, v84
	v_div_scale_f32 v79, s[2:3], v78, v78, v63
	v_fma_f32 v68, -v83, v70, v68
	v_rcp_f32_e32 v82, v79
	v_div_fmas_f32 v68, v68, v84, v70
	v_div_fixup_f32 v58, v68, v81, v58
	v_mul_f32_e32 v68, v58, v77
	v_mul_f32_e32 v77, 0xbfb8aa3b, v59
	v_fma_f32 v58, -v79, v82, 1.0
	v_exp_f32_e32 v77, v77
	v_fmac_f32_e32 v82, v58, v82
	v_div_scale_f32 v58, vcc, v63, v78, v63
	v_mul_f32_e32 v70, v58, v82
	v_fma_f32 v81, -v79, v70, v58
	v_fmac_f32_e32 v70, v81, v82
	v_add_f32_e32 v77, 1.0, v77
	v_fma_f32 v58, -v79, v70, v58
	v_div_scale_f32 v79, s[2:3], v77, v77, v59
	v_rcp_f32_e32 v81, v79
	v_div_fmas_f32 v58, v58, v82, v70
	v_mul_f32_e32 v70, 0xbfb8aa3b, v64
	v_div_fixup_f32 v58, v58, v78, v63
	v_fma_f32 v63, -v79, v81, 1.0
	v_exp_f32_e32 v70, v70
	v_fmac_f32_e32 v81, v63, v81
	v_div_scale_f32 v63, vcc, v59, v77, v59
	v_mul_f32_e32 v58, v58, v69
	v_mul_f32_e32 v69, v63, v81
	v_fma_f32 v78, -v79, v69, v63
	v_fmac_f32_e32 v69, v78, v81
	v_add_f32_e32 v70, 1.0, v70
	v_fma_f32 v63, -v79, v69, v63
	v_div_scale_f32 v78, s[2:3], v70, v70, v64
	v_rcp_f32_e32 v79, v78
	v_div_fmas_f32 v63, v63, v81, v69
	v_div_fixup_f32 v59, v63, v77, v59
	v_mul_f32_e32 v63, v59, v72
	v_mul_f32_e32 v72, 0xbfb8aa3b, v60
	v_exp_f32_e32 v72, v72
	v_fma_f32 v59, -v78, v79, 1.0
	v_fmac_f32_e32 v79, v59, v79
	v_div_scale_f32 v59, vcc, v64, v70, v64
	v_mul_f32_e32 v69, v59, v79
	v_fma_f32 v77, -v78, v69, v59
	v_add_f32_e32 v72, 1.0, v72
	v_fmac_f32_e32 v69, v77, v79
	v_div_scale_f32 v77, s[2:3], v72, v72, v60
	v_fma_f32 v59, -v78, v69, v59
	v_rcp_f32_e32 v78, v77
	v_div_fmas_f32 v59, v59, v79, v69
	v_div_fixup_f32 v59, v59, v70, v64
	v_mul_f32_e32 v70, 0xbfb8aa3b, v65
	v_exp_f32_e32 v70, v70
	v_fma_f32 v64, -v77, v78, 1.0
	v_fmac_f32_e32 v78, v64, v78
	v_div_scale_f32 v64, vcc, v60, v72, v60
	v_mul_f32_e32 v69, v64, v78
	v_mul_f32_e32 v59, v59, v76
	v_fma_f32 v76, -v77, v69, v64
	v_add_f32_e32 v70, 1.0, v70
	v_fmac_f32_e32 v69, v76, v78
	v_div_scale_f32 v76, s[2:3], v70, v70, v65
	v_fma_f32 v64, -v77, v69, v64
	v_rcp_f32_e32 v77, v76
	v_div_fmas_f32 v64, v64, v78, v69
	v_div_fixup_f32 v60, v64, v72, v60
	v_mul_f32_e32 v72, 0xbfb8aa3b, v61
	v_mul_f32_e32 v64, v60, v80
	v_fma_f32 v60, -v76, v77, 1.0
	v_exp_f32_e32 v72, v72
	v_fmac_f32_e32 v77, v60, v77
	v_div_scale_f32 v60, vcc, v65, v70, v65
	v_mul_f32_e32 v69, v60, v77
	v_fma_f32 v78, -v76, v69, v60
	v_fmac_f32_e32 v69, v78, v77
	v_add_f32_e32 v72, 1.0, v72
	v_fma_f32 v60, -v76, v69, v60
	v_div_scale_f32 v76, s[2:3], v72, v72, v61
	v_rcp_f32_e32 v78, v76
	v_div_fmas_f32 v60, v60, v77, v69
	v_div_fixup_f32 v60, v60, v70, v65
	v_mul_f32_e32 v60, v60, v71
	v_fma_f32 v65, -v76, v78, 1.0
	v_fmac_f32_e32 v78, v65, v78
	v_div_scale_f32 v65, vcc, v61, v72, v61
	v_mul_f32_e32 v69, v65, v78
	v_fma_f32 v70, -v76, v69, v65
	v_fmac_f32_e32 v69, v70, v78
	v_fma_f32 v65, -v76, v69, v65
	v_div_fmas_f32 v65, v65, v78, v69
	v_div_fixup_f32 v61, v65, v72, v61
	v_mul_f32_e32 v61, v61, v73
	v_cvt_pk_bf16_f32 v58, v62, v58
	v_cvt_pk_bf16_f32 v59, v59, v60
	v_cvt_pk_bf16_f32 v60, v68, v63
	v_cvt_pk_bf16_f32 v61, v64, v61
	v_mul_f32_e32 v73, 0xbfb8aa3b, v50
	global_store_dwordx4 v[74:75], v[58:61], off
	v_exp_f32_e32 v73, v73
	s_waitcnt vmcnt(14)
;     __device__ __forceinline__ void operator()(const f32x4 (&acc)[2][2][4][2], const Unit& u, int wr, int wc, int fr, int fq) const {
;         const int row0 = u.pm * BM + wr * 64 + fr, col0 = u.pn * BM + wc * 32 + 8 * fq;
; #pragma unroll
;         for (int ai = 0; ai < 2; ++ai)
; #pragma unroll
;             for (int m = 0; m < 4; ++m)
; #pragma unroll
;                 for (int bj = 0; bj < 2; ++bj) f(row0 + ai * HALF + m * 16, col0 + bj * HALF, acc[ai][bj][m][0], acc[ai][bj][m][1]);
	v_mov_b32_e32 v62, v222
	v_mov_b32_e32 v63, v223
	v_mov_b32_e32 v64, v224
	v_mov_b32_e32 v65, v225
	v_lshlrev_b32_e32 v70, 16, v65
	v_mul_f32_e32 v60, 0xbfb8aa3b, v54
	v_exp_f32_e32 v60, v60
	v_lshlrev_b32_e32 v58, 16, v62
	v_and_b32_e32 v59, 0xffff0000, v62
	v_lshlrev_b32_e32 v61, 16, v63
	v_add_f32_e32 v60, 1.0, v60
	v_div_scale_f32 v68, s[2:3], v60, v60, v54
	v_rcp_f32_e32 v69, v68
	v_and_b32_e32 v62, 0xffff0000, v63
	v_lshlrev_b32_e32 v63, 16, v64
	v_and_b32_e32 v64, 0xffff0000, v64
	v_fma_f32 v71, -v68, v69, 1.0
	v_fmac_f32_e32 v69, v71, v69
	v_div_scale_f32 v71, vcc, v54, v60, v54
	v_mul_f32_e32 v72, v71, v69
	v_fma_f32 v74, -v68, v72, v71
	v_fmac_f32_e32 v72, v74, v69
	v_fma_f32 v68, -v68, v72, v71
	v_add_f32_e32 v71, 1.0, v73
	v_div_scale_f32 v73, s[2:3], v71, v71, v50
	v_rcp_f32_e32 v74, v73
	v_div_fmas_f32 v68, v68, v69, v72
	v_div_fixup_f32 v54, v68, v60, v54
	v_mul_f32_e32 v68, 0xbfb8aa3b, v55
	v_exp_f32_e32 v68, v68
	v_mul_f32_e32 v54, v54, v58
	v_fma_f32 v58, -v73, v74, 1.0
	v_fmac_f32_e32 v74, v58, v74
	v_div_scale_f32 v58, vcc, v50, v71, v50
	v_mul_f32_e32 v60, v58, v74
	v_fma_f32 v69, -v73, v60, v58
	v_add_f32_e32 v68, 1.0, v68
	v_fmac_f32_e32 v60, v69, v74
	v_div_scale_f32 v69, s[2:3], v68, v68, v55
	v_fma_f32 v58, -v73, v60, v58
	v_rcp_f32_e32 v72, v69
	v_div_fmas_f32 v58, v58, v74, v60
	v_div_fixup_f32 v50, v58, v71, v50
	v_mul_f32_e32 v58, v50, v63
	v_mul_f32_e32 v63, 0xbfb8aa3b, v51
	v_fma_f32 v50, -v69, v72, 1.0
	v_exp_f32_e32 v63, v63
	v_fmac_f32_e32 v72, v50, v72
	v_div_scale_f32 v50, vcc, v55, v68, v55
	v_mul_f32_e32 v60, v50, v72
	v_fma_f32 v71, -v69, v60, v50
	v_fmac_f32_e32 v60, v71, v72
	v_add_f32_e32 v63, 1.0, v63
	v_fma_f32 v50, -v69, v60, v50
	v_div_scale_f32 v69, s[2:3], v63, v63, v51
	v_rcp_f32_e32 v71, v69
	v_div_fmas_f32 v50, v50, v72, v60
	v_mul_f32_e32 v60, 0xbfb8aa3b, v56
	v_exp_f32_e32 v60, v60
	v_div_fixup_f32 v50, v50, v68, v55
	v_fma_f32 v55, -v69, v71, 1.0
	v_fmac_f32_e32 v71, v55, v71
	v_div_scale_f32 v55, vcc, v51, v63, v51
	v_mul_f32_e32 v50, v50, v59
	v_mul_f32_e32 v59, v55, v71
	v_fma_f32 v68, -v69, v59, v55
	v_add_f32_e32 v60, 1.0, v60
	v_fmac_f32_e32 v59, v68, v71
	v_div_scale_f32 v68, s[2:3], v60, v60, v56
	v_fma_f32 v55, -v69, v59, v55
	v_rcp_f32_e32 v69, v68
	v_div_fmas_f32 v55, v55, v71, v59
	v_div_fixup_f32 v51, v55, v63, v51
	v_mul_f32_e32 v63, 0xbfb8aa3b, v52
	v_exp_f32_e32 v63, v63
	v_mul_f32_e32 v55, v51, v64
	v_fma_f32 v51, -v68, v69, 1.0
	v_fmac_f32_e32 v69, v51, v69
	v_div_scale_f32 v51, vcc, v56, v60, v56
	v_mul_f32_e32 v59, v51, v69
	v_fma_f32 v64, -v68, v59, v51
	v_add_f32_e32 v63, 1.0, v63
	v_fmac_f32_e32 v59, v64, v69
	v_div_scale_f32 v64, s[2:3], v63, v63, v52
	v_fma_f32 v51, -v68, v59, v51
	v_rcp_f32_e32 v68, v64
	v_div_fmas_f32 v51, v51, v69, v59
	v_div_fixup_f32 v51, v51, v60, v56
	v_mul_f32_e32 v60, 0xbfb8aa3b, v57
	v_exp_f32_e32 v60, v60
	v_fma_f32 v56, -v64, v68, 1.0
	v_fmac_f32_e32 v68, v56, v68
	v_div_scale_f32 v56, vcc, v52, v63, v52
	v_mul_f32_e32 v59, v56, v68
	v_mul_f32_e32 v51, v51, v61
	v_fma_f32 v61, -v64, v59, v56
	v_add_f32_e32 v60, 1.0, v60
	v_fmac_f32_e32 v59, v61, v68
	v_div_scale_f32 v61, s[2:3], v60, v60, v57
	v_fma_f32 v56, -v64, v59, v56
	v_rcp_f32_e32 v64, v61
	v_div_fmas_f32 v56, v56, v68, v59
	v_div_fixup_f32 v52, v56, v63, v52
	v_mul_f32_e32 v56, v52, v70
	v_fma_f32 v52, -v61, v64, 1.0
	v_mul_f32_e32 v63, 0xbfb8aa3b, v53
	v_fmac_f32_e32 v64, v52, v64
	v_div_scale_f32 v52, vcc, v57, v60, v57
	v_exp_f32_e32 v63, v63
	v_mul_f32_e32 v59, v52, v64
	v_fma_f32 v68, -v61, v59, v52
	v_fmac_f32_e32 v59, v68, v64
	v_fma_f32 v52, -v61, v59, v52
	v_add_f32_e32 v61, 1.0, v63
	v_div_scale_f32 v63, s[2:3], v61, v61, v53
	v_rcp_f32_e32 v68, v63
	v_div_fmas_f32 v52, v52, v64, v59
	v_div_fixup_f32 v52, v52, v60, v57
	v_mul_f32_e32 v52, v52, v62
	v_fma_f32 v57, -v63, v68, 1.0
	v_fmac_f32_e32 v68, v57, v68
	v_div_scale_f32 v57, vcc, v53, v61, v53
	v_mul_f32_e32 v59, v57, v68
	v_fma_f32 v60, -v63, v59, v57
	v_fmac_f32_e32 v59, v60, v68
	v_fma_f32 v57, -v63, v59, v57
	v_div_fmas_f32 v57, v57, v68, v59
	v_and_b32_e32 v65, 0xffff0000, v65
	v_div_fixup_f32 v53, v57, v61, v53
	v_cvt_pk_bf16_f32 v50, v54, v50
	v_cvt_pk_bf16_f32 v51, v51, v52
	v_cvt_pk_bf16_f32 v52, v58, v55
	v_add_co_u32_e32 v58, vcc, s49, v148
	v_mul_f32_e32 v53, v53, v65
	s_nop 0
	v_addc_co_u32_e32 v59, vcc, 0, v149, vcc
	v_cvt_pk_bf16_f32 v53, v56, v53
	s_waitcnt vmcnt(14)
;     __device__ __forceinline__ void operator()(const f32x4 (&acc)[2][2][4][2], const Unit& u, int wr, int wc, int fr, int fq) const {
;         const int row0 = u.pm * BM + wr * 64 + fr, col0 = u.pn * BM + wc * 32 + 8 * fq;
; #pragma unroll
;         for (int ai = 0; ai < 2; ++ai)
; #pragma unroll
;             for (int m = 0; m < 4; ++m)
; #pragma unroll
;                 for (int bj = 0; bj < 2; ++bj) f(row0 + ai * HALF + m * 16, col0 + bj * HALF, acc[ai][bj][m][0], acc[ai][bj][m][1]);
	v_mov_b32_e32 v54, v226
	v_mov_b32_e32 v55, v227
	v_mov_b32_e32 v56, v228
	v_mov_b32_e32 v57, v229
	v_lshlrev_b32_e32 v61, 16, v56
	global_store_dwordx4 v[66:67], v[50:53], off offset:256
	v_mul_f32_e32 v67, 0xbfb8aa3b, v42
	v_exp_f32_e32 v67, v67
	v_lshlrev_b32_e32 v52, 16, v54
	v_and_b32_e32 v53, 0xffff0000, v54
	v_mul_f32_e32 v54, 0xbfb8aa3b, v46
	v_exp_f32_e32 v54, v54
	v_and_b32_e32 v56, 0xffff0000, v56
	v_lshlrev_b32_e32 v60, 16, v55
	v_lshlrev_b32_e32 v64, 16, v57
	v_add_f32_e32 v54, 1.0, v54
	v_div_scale_f32 v62, s[2:3], v54, v54, v46
	v_rcp_f32_e32 v63, v62
	v_and_b32_e32 v55, 0xffff0000, v55
	v_and_b32_e32 v57, 0xffff0000, v57
	v_lshl_add_u64 v[50:51], v[148:149], 0, s[16:17]
	v_fma_f32 v65, -v62, v63, 1.0
	v_fmac_f32_e32 v63, v65, v63
	v_div_scale_f32 v65, vcc, v46, v54, v46
	v_mul_f32_e32 v66, v65, v63
	v_fma_f32 v68, -v62, v66, v65
	v_fmac_f32_e32 v66, v68, v63
	v_fma_f32 v62, -v62, v66, v65
	v_add_f32_e32 v65, 1.0, v67
	v_div_scale_f32 v67, s[2:3], v65, v65, v42
	v_rcp_f32_e32 v68, v67
	v_div_fmas_f32 v62, v62, v63, v66
	v_div_fixup_f32 v46, v62, v54, v46
	v_mul_f32_e32 v62, 0xbfb8aa3b, v47
	v_exp_f32_e32 v62, v62
	v_mul_f32_e32 v46, v46, v52
	v_fma_f32 v52, -v67, v68, 1.0
	v_fmac_f32_e32 v68, v52, v68
	v_div_scale_f32 v52, vcc, v42, v65, v42
	v_mul_f32_e32 v54, v52, v68
	v_fma_f32 v63, -v67, v54, v52
	v_add_f32_e32 v62, 1.0, v62
	v_fmac_f32_e32 v54, v63, v68
	v_div_scale_f32 v63, s[2:3], v62, v62, v47
	v_fma_f32 v52, -v67, v54, v52
	v_rcp_f32_e32 v66, v63
	v_div_fmas_f32 v52, v52, v68, v54
	v_div_fixup_f32 v42, v52, v65, v42
	v_mul_f32_e32 v52, v42, v61
	v_mul_f32_e32 v61, 0xbfb8aa3b, v43
	v_fma_f32 v42, -v63, v66, 1.0
	v_exp_f32_e32 v61, v61
	v_fmac_f32_e32 v66, v42, v66
	v_div_scale_f32 v42, vcc, v47, v62, v47
	v_mul_f32_e32 v54, v42, v66
	v_fma_f32 v65, -v63, v54, v42
	v_fmac_f32_e32 v54, v65, v66
	v_add_f32_e32 v61, 1.0, v61
	v_fma_f32 v42, -v63, v54, v42
	v_div_scale_f32 v63, s[2:3], v61, v61, v43
	v_rcp_f32_e32 v65, v63
	v_div_fmas_f32 v42, v42, v66, v54
	v_mul_f32_e32 v54, 0xbfb8aa3b, v48
	v_div_fixup_f32 v42, v42, v62, v47
	v_fma_f32 v47, -v63, v65, 1.0
	v_exp_f32_e32 v54, v54
	v_fmac_f32_e32 v65, v47, v65
	v_div_scale_f32 v47, vcc, v43, v61, v43
	v_mul_f32_e32 v42, v42, v53
	v_mul_f32_e32 v53, v47, v65
	v_fma_f32 v62, -v63, v53, v47
	v_fmac_f32_e32 v53, v62, v65
	v_add_f32_e32 v54, 1.0, v54
	v_fma_f32 v47, -v63, v53, v47
	v_div_scale_f32 v62, s[2:3], v54, v54, v48
	v_rcp_f32_e32 v63, v62
	v_div_fmas_f32 v47, v47, v65, v53
	v_div_fixup_f32 v43, v47, v61, v43
	v_mul_f32_e32 v47, v43, v56
	v_mul_f32_e32 v56, 0xbfb8aa3b, v44
	v_exp_f32_e32 v56, v56
	v_fma_f32 v43, -v62, v63, 1.0
	v_fmac_f32_e32 v63, v43, v63
	v_div_scale_f32 v43, vcc, v48, v54, v48
	v_mul_f32_e32 v53, v43, v63
	v_fma_f32 v61, -v62, v53, v43
	v_add_f32_e32 v56, 1.0, v56
	v_fmac_f32_e32 v53, v61, v63
	v_div_scale_f32 v61, s[2:3], v56, v56, v44
	v_fma_f32 v43, -v62, v53, v43
	v_rcp_f32_e32 v62, v61
	v_div_fmas_f32 v43, v43, v63, v53
	v_div_fixup_f32 v43, v43, v54, v48
	v_mul_f32_e32 v54, 0xbfb8aa3b, v49
	v_exp_f32_e32 v54, v54
	v_fma_f32 v48, -v61, v62, 1.0
	v_fmac_f32_e32 v62, v48, v62
	v_div_scale_f32 v48, vcc, v44, v56, v44
	v_mul_f32_e32 v53, v48, v62
	v_mul_f32_e32 v43, v43, v60
	v_fma_f32 v60, -v61, v53, v48
	v_add_f32_e32 v54, 1.0, v54
	v_fmac_f32_e32 v53, v60, v62
	v_div_scale_f32 v60, s[2:3], v54, v54, v49
	v_fma_f32 v48, -v61, v53, v48
	v_rcp_f32_e32 v61, v60
	v_div_fmas_f32 v48, v48, v62, v53
	v_div_fixup_f32 v44, v48, v56, v44
	v_mul_f32_e32 v56, 0xbfb8aa3b, v45
	v_mul_f32_e32 v48, v44, v64
	v_fma_f32 v44, -v60, v61, 1.0
	v_exp_f32_e32 v56, v56
	v_fmac_f32_e32 v61, v44, v61
	v_div_scale_f32 v44, vcc, v49, v54, v49
	v_mul_f32_e32 v53, v44, v61
	v_fma_f32 v62, -v60, v53, v44
	v_fmac_f32_e32 v53, v62, v61
	v_add_f32_e32 v56, 1.0, v56
	v_fma_f32 v44, -v60, v53, v44
	v_div_scale_f32 v60, s[2:3], v56, v56, v45
	v_rcp_f32_e32 v62, v60
	v_div_fmas_f32 v44, v44, v61, v53
	v_div_fixup_f32 v44, v44, v54, v49
	v_mul_f32_e32 v44, v44, v55
	v_fma_f32 v49, -v60, v62, 1.0
	v_fmac_f32_e32 v62, v49, v62
	v_div_scale_f32 v49, vcc, v45, v56, v45
	v_mul_f32_e32 v53, v49, v62
	v_fma_f32 v54, -v60, v53, v49
	v_fmac_f32_e32 v53, v54, v62
	v_fma_f32 v49, -v60, v53, v49
	v_div_fmas_f32 v49, v49, v62, v53
	v_div_fixup_f32 v45, v49, v56, v45
	v_mul_f32_e32 v45, v45, v57
	v_cvt_pk_bf16_f32 v42, v46, v42
	v_cvt_pk_bf16_f32 v43, v43, v44
	v_cvt_pk_bf16_f32 v44, v52, v47
	v_cvt_pk_bf16_f32 v45, v48, v45
	v_mul_f32_e32 v57, 0xbfb8aa3b, v34
	global_store_dwordx4 v[58:59], v[42:45], off
	v_exp_f32_e32 v57, v57
	s_waitcnt vmcnt(14)
;     __device__ __forceinline__ void operator()(const f32x4 (&acc)[2][2][4][2], const Unit& u, int wr, int wc, int fr, int fq) const {
;         const int row0 = u.pm * BM + wr * 64 + fr, col0 = u.pn * BM + wc * 32 + 8 * fq;
; #pragma unroll
;         for (int ai = 0; ai < 2; ++ai)
; #pragma unroll
;             for (int m = 0; m < 4; ++m)
; #pragma unroll
;                 for (int bj = 0; bj < 2; ++bj) f(row0 + ai * HALF + m * 16, col0 + bj * HALF, acc[ai][bj][m][0], acc[ai][bj][m][1]);
	v_mov_b32_e32 v46, v230
	v_mov_b32_e32 v47, v231
	v_mov_b32_e32 v48, v232
	v_mov_b32_e32 v49, v233
	v_lshlrev_b32_e32 v54, 16, v49
	v_mul_f32_e32 v44, 0xbfb8aa3b, v38
	v_exp_f32_e32 v44, v44
	v_lshlrev_b32_e32 v42, 16, v46
	v_and_b32_e32 v43, 0xffff0000, v46
	v_lshlrev_b32_e32 v45, 16, v47
	v_add_f32_e32 v44, 1.0, v44
	v_div_scale_f32 v52, s[2:3], v44, v44, v38
	v_rcp_f32_e32 v53, v52
	v_and_b32_e32 v46, 0xffff0000, v47
	v_lshlrev_b32_e32 v47, 16, v48
	v_and_b32_e32 v48, 0xffff0000, v48
	v_fma_f32 v55, -v52, v53, 1.0
	v_fmac_f32_e32 v53, v55, v53
	v_div_scale_f32 v55, vcc, v38, v44, v38
	v_mul_f32_e32 v56, v55, v53
	v_fma_f32 v58, -v52, v56, v55
	v_fmac_f32_e32 v56, v58, v53
	v_fma_f32 v52, -v52, v56, v55
	v_add_f32_e32 v55, 1.0, v57
	v_div_scale_f32 v57, s[2:3], v55, v55, v34
	v_rcp_f32_e32 v58, v57
	v_div_fmas_f32 v52, v52, v53, v56
	v_div_fixup_f32 v38, v52, v44, v38
	v_mul_f32_e32 v52, 0xbfb8aa3b, v39
	v_exp_f32_e32 v52, v52
	v_mul_f32_e32 v38, v38, v42
	v_fma_f32 v42, -v57, v58, 1.0
	v_fmac_f32_e32 v58, v42, v58
	v_div_scale_f32 v42, vcc, v34, v55, v34
	v_mul_f32_e32 v44, v42, v58
	v_fma_f32 v53, -v57, v44, v42
	v_add_f32_e32 v52, 1.0, v52
	v_fmac_f32_e32 v44, v53, v58
	v_div_scale_f32 v53, s[2:3], v52, v52, v39
	v_fma_f32 v42, -v57, v44, v42
	v_rcp_f32_e32 v56, v53
	v_div_fmas_f32 v42, v42, v58, v44
	v_div_fixup_f32 v34, v42, v55, v34
	v_mul_f32_e32 v42, v34, v47
	v_mul_f32_e32 v47, 0xbfb8aa3b, v35
	v_fma_f32 v34, -v53, v56, 1.0
	v_exp_f32_e32 v47, v47
	v_fmac_f32_e32 v56, v34, v56
	v_div_scale_f32 v34, vcc, v39, v52, v39
	v_mul_f32_e32 v44, v34, v56
	v_fma_f32 v55, -v53, v44, v34
	v_fmac_f32_e32 v44, v55, v56
	v_add_f32_e32 v47, 1.0, v47
	v_fma_f32 v34, -v53, v44, v34
	v_div_scale_f32 v53, s[2:3], v47, v47, v35
	v_rcp_f32_e32 v55, v53
	v_div_fmas_f32 v34, v34, v56, v44
	v_mul_f32_e32 v44, 0xbfb8aa3b, v40
	v_exp_f32_e32 v44, v44
	v_div_fixup_f32 v34, v34, v52, v39
	v_fma_f32 v39, -v53, v55, 1.0
	v_fmac_f32_e32 v55, v39, v55
	v_div_scale_f32 v39, vcc, v35, v47, v35
	v_mul_f32_e32 v34, v34, v43
	v_mul_f32_e32 v43, v39, v55
	v_fma_f32 v52, -v53, v43, v39
	v_add_f32_e32 v44, 1.0, v44
	v_fmac_f32_e32 v43, v52, v55
	v_div_scale_f32 v52, s[2:3], v44, v44, v40
	v_fma_f32 v39, -v53, v43, v39
	v_rcp_f32_e32 v53, v52
	v_div_fmas_f32 v39, v39, v55, v43
	v_div_fixup_f32 v35, v39, v47, v35
	v_mul_f32_e32 v47, 0xbfb8aa3b, v36
	v_exp_f32_e32 v47, v47
	v_mul_f32_e32 v39, v35, v48
	v_fma_f32 v35, -v52, v53, 1.0
	v_fmac_f32_e32 v53, v35, v53
	v_div_scale_f32 v35, vcc, v40, v44, v40
	v_mul_f32_e32 v43, v35, v53
	v_fma_f32 v48, -v52, v43, v35
	v_add_f32_e32 v47, 1.0, v47
	v_fmac_f32_e32 v43, v48, v53
	v_div_scale_f32 v48, s[2:3], v47, v47, v36
	v_fma_f32 v35, -v52, v43, v35
	v_rcp_f32_e32 v52, v48
	v_div_fmas_f32 v35, v35, v53, v43
	v_div_fixup_f32 v35, v35, v44, v40
	v_mul_f32_e32 v44, 0xbfb8aa3b, v41
	v_exp_f32_e32 v44, v44
	v_fma_f32 v40, -v48, v52, 1.0
	v_fmac_f32_e32 v52, v40, v52
	v_div_scale_f32 v40, vcc, v36, v47, v36
	v_mul_f32_e32 v43, v40, v52
	v_mul_f32_e32 v35, v35, v45
	v_fma_f32 v45, -v48, v43, v40
	v_add_f32_e32 v44, 1.0, v44
	v_fmac_f32_e32 v43, v45, v52
	v_div_scale_f32 v45, s[2:3], v44, v44, v41
	v_fma_f32 v40, -v48, v43, v40
	v_rcp_f32_e32 v48, v45
	v_div_fmas_f32 v40, v40, v52, v43
	v_div_fixup_f32 v36, v40, v47, v36
	v_mul_f32_e32 v40, v36, v54
	v_fma_f32 v36, -v45, v48, 1.0
	v_mul_f32_e32 v47, 0xbfb8aa3b, v37
	v_fmac_f32_e32 v48, v36, v48
	v_div_scale_f32 v36, vcc, v41, v44, v41
	v_exp_f32_e32 v47, v47
	v_mul_f32_e32 v43, v36, v48
	v_fma_f32 v52, -v45, v43, v36
	v_fmac_f32_e32 v43, v52, v48
	v_fma_f32 v36, -v45, v43, v36
	v_add_f32_e32 v45, 1.0, v47
	v_div_scale_f32 v47, s[2:3], v45, v45, v37
	v_rcp_f32_e32 v52, v47
	v_div_fmas_f32 v36, v36, v48, v43
	v_div_fixup_f32 v36, v36, v44, v41
	v_mul_f32_e32 v36, v36, v46
	v_fma_f32 v41, -v47, v52, 1.0
	v_fmac_f32_e32 v52, v41, v52
	v_div_scale_f32 v41, vcc, v37, v45, v37
	v_mul_f32_e32 v43, v41, v52
	v_fma_f32 v44, -v47, v43, v41
	v_fmac_f32_e32 v43, v44, v52
	v_fma_f32 v41, -v47, v43, v41
	v_div_fmas_f32 v41, v41, v52, v43
	v_and_b32_e32 v49, 0xffff0000, v49
	v_div_fixup_f32 v37, v41, v45, v37
	v_cvt_pk_bf16_f32 v34, v38, v34
	v_cvt_pk_bf16_f32 v35, v35, v36
	v_cvt_pk_bf16_f32 v36, v42, v39
	v_add_co_u32_e32 v42, vcc, s50, v148
	v_mul_f32_e32 v37, v37, v49
	s_nop 0
	v_addc_co_u32_e32 v43, vcc, 0, v149, vcc
	v_cvt_pk_bf16_f32 v37, v40, v37
	s_waitcnt vmcnt(14)
;     __device__ __forceinline__ void operator()(const f32x4 (&acc)[2][2][4][2], const Unit& u, int wr, int wc, int fr, int fq) const {
;         const int row0 = u.pm * BM + wr * 64 + fr, col0 = u.pn * BM + wc * 32 + 8 * fq;
; #pragma unroll
;         for (int ai = 0; ai < 2; ++ai)
; #pragma unroll
;             for (int m = 0; m < 4; ++m)
; #pragma unroll
;                 for (int bj = 0; bj < 2; ++bj) f(row0 + ai * HALF + m * 16, col0 + bj * HALF, acc[ai][bj][m][0], acc[ai][bj][m][1]);
	v_mov_b32_e32 v38, v234
	v_mov_b32_e32 v39, v235
	v_mov_b32_e32 v40, v236
	v_mov_b32_e32 v41, v237
	v_lshlrev_b32_e32 v45, 16, v40
	global_store_dwordx4 v[50:51], v[34:37], off offset:256
	v_mul_f32_e32 v51, 0xbfb8aa3b, v26
	v_exp_f32_e32 v51, v51
	v_lshlrev_b32_e32 v36, 16, v38
	v_and_b32_e32 v37, 0xffff0000, v38
	v_mul_f32_e32 v38, 0xbfb8aa3b, v30
	v_exp_f32_e32 v38, v38
	v_and_b32_e32 v40, 0xffff0000, v40
	v_lshlrev_b32_e32 v44, 16, v39
	v_lshlrev_b32_e32 v48, 16, v41
	v_add_f32_e32 v38, 1.0, v38
	v_div_scale_f32 v46, s[2:3], v38, v38, v30
	v_rcp_f32_e32 v47, v46
	v_and_b32_e32 v39, 0xffff0000, v39
	v_and_b32_e32 v41, 0xffff0000, v41
	v_lshl_add_u64 v[34:35], v[148:149], 0, s[18:19]
	v_fma_f32 v49, -v46, v47, 1.0
	v_fmac_f32_e32 v47, v49, v47
	v_div_scale_f32 v49, vcc, v30, v38, v30
	v_mul_f32_e32 v50, v49, v47
	v_fma_f32 v52, -v46, v50, v49
	v_fmac_f32_e32 v50, v52, v47
	v_fma_f32 v46, -v46, v50, v49
	v_add_f32_e32 v49, 1.0, v51
	v_div_scale_f32 v51, s[2:3], v49, v49, v26
	v_rcp_f32_e32 v52, v51
	v_div_fmas_f32 v46, v46, v47, v50
	v_div_fixup_f32 v30, v46, v38, v30
	v_mul_f32_e32 v46, 0xbfb8aa3b, v31
	v_exp_f32_e32 v46, v46
	v_mul_f32_e32 v30, v30, v36
	v_fma_f32 v36, -v51, v52, 1.0
	v_fmac_f32_e32 v52, v36, v52
	v_div_scale_f32 v36, vcc, v26, v49, v26
	v_mul_f32_e32 v38, v36, v52
	v_fma_f32 v47, -v51, v38, v36
	v_add_f32_e32 v46, 1.0, v46
	v_fmac_f32_e32 v38, v47, v52
	v_div_scale_f32 v47, s[2:3], v46, v46, v31
	v_fma_f32 v36, -v51, v38, v36
	v_rcp_f32_e32 v50, v47
	v_div_fmas_f32 v36, v36, v52, v38
	v_div_fixup_f32 v26, v36, v49, v26
	v_mul_f32_e32 v36, v26, v45
	v_mul_f32_e32 v45, 0xbfb8aa3b, v27
	v_fma_f32 v26, -v47, v50, 1.0
	v_exp_f32_e32 v45, v45
	v_fmac_f32_e32 v50, v26, v50
	v_div_scale_f32 v26, vcc, v31, v46, v31
	v_mul_f32_e32 v38, v26, v50
	v_fma_f32 v49, -v47, v38, v26
	v_fmac_f32_e32 v38, v49, v50
	v_add_f32_e32 v45, 1.0, v45
	v_fma_f32 v26, -v47, v38, v26
	v_div_scale_f32 v47, s[2:3], v45, v45, v27
	v_rcp_f32_e32 v49, v47
	v_div_fmas_f32 v26, v26, v50, v38
	v_mul_f32_e32 v38, 0xbfb8aa3b, v32
	v_div_fixup_f32 v26, v26, v46, v31
	v_fma_f32 v31, -v47, v49, 1.0
	v_exp_f32_e32 v38, v38
	v_fmac_f32_e32 v49, v31, v49
	v_div_scale_f32 v31, vcc, v27, v45, v27
	v_mul_f32_e32 v26, v26, v37
	v_mul_f32_e32 v37, v31, v49
	v_fma_f32 v46, -v47, v37, v31
	v_fmac_f32_e32 v37, v46, v49
	v_add_f32_e32 v38, 1.0, v38
	v_fma_f32 v31, -v47, v37, v31
	v_div_scale_f32 v46, s[2:3], v38, v38, v32
	v_rcp_f32_e32 v47, v46
	v_div_fmas_f32 v31, v31, v49, v37
	v_div_fixup_f32 v27, v31, v45, v27
	v_mul_f32_e32 v31, v27, v40
	v_mul_f32_e32 v40, 0xbfb8aa3b, v28
	v_exp_f32_e32 v40, v40
	v_fma_f32 v27, -v46, v47, 1.0
	v_fmac_f32_e32 v47, v27, v47
	v_div_scale_f32 v27, vcc, v32, v38, v32
	v_mul_f32_e32 v37, v27, v47
	v_fma_f32 v45, -v46, v37, v27
	v_add_f32_e32 v40, 1.0, v40
	v_fmac_f32_e32 v37, v45, v47
	v_div_scale_f32 v45, s[2:3], v40, v40, v28
	v_fma_f32 v27, -v46, v37, v27
	v_rcp_f32_e32 v46, v45
	v_div_fmas_f32 v27, v27, v47, v37
	v_div_fixup_f32 v27, v27, v38, v32
	v_mul_f32_e32 v38, 0xbfb8aa3b, v33
	v_exp_f32_e32 v38, v38
	v_fma_f32 v32, -v45, v46, 1.0
	v_fmac_f32_e32 v46, v32, v46
	v_div_scale_f32 v32, vcc, v28, v40, v28
	v_mul_f32_e32 v37, v32, v46
	v_mul_f32_e32 v27, v27, v44
	v_fma_f32 v44, -v45, v37, v32
	v_add_f32_e32 v38, 1.0, v38
	v_fmac_f32_e32 v37, v44, v46
	v_div_scale_f32 v44, s[2:3], v38, v38, v33
	v_fma_f32 v32, -v45, v37, v32
	v_rcp_f32_e32 v45, v44
	v_div_fmas_f32 v32, v32, v46, v37
	v_div_fixup_f32 v28, v32, v40, v28
	v_mul_f32_e32 v40, 0xbfb8aa3b, v29
	v_mul_f32_e32 v32, v28, v48
	v_fma_f32 v28, -v44, v45, 1.0
	v_exp_f32_e32 v40, v40
	v_fmac_f32_e32 v45, v28, v45
	v_div_scale_f32 v28, vcc, v33, v38, v33
	v_mul_f32_e32 v37, v28, v45
	v_fma_f32 v46, -v44, v37, v28
	v_fmac_f32_e32 v37, v46, v45
	v_add_f32_e32 v40, 1.0, v40
	v_fma_f32 v28, -v44, v37, v28
	v_div_scale_f32 v44, s[2:3], v40, v40, v29
	v_rcp_f32_e32 v46, v44
	v_div_fmas_f32 v28, v28, v45, v37
	v_div_fixup_f32 v28, v28, v38, v33
	v_mul_f32_e32 v28, v28, v39
	v_fma_f32 v33, -v44, v46, 1.0
	v_fmac_f32_e32 v46, v33, v46
	v_div_scale_f32 v33, vcc, v29, v40, v29
	v_mul_f32_e32 v37, v33, v46
	v_fma_f32 v38, -v44, v37, v33
	v_fmac_f32_e32 v37, v38, v46
	v_fma_f32 v33, -v44, v37, v33
	v_div_fmas_f32 v33, v33, v46, v37
	v_div_fixup_f32 v29, v33, v40, v29
	v_mul_f32_e32 v29, v29, v41
	v_cvt_pk_bf16_f32 v26, v30, v26
	v_cvt_pk_bf16_f32 v27, v27, v28
	v_cvt_pk_bf16_f32 v28, v36, v31
	v_cvt_pk_bf16_f32 v29, v32, v29
	v_mul_f32_e32 v41, 0xbfb8aa3b, v18
	global_store_dwordx4 v[42:43], v[26:29], off
	v_exp_f32_e32 v41, v41
	s_waitcnt vmcnt(14)
;     __device__ __forceinline__ void operator()(const f32x4 (&acc)[2][2][4][2], const Unit& u, int wr, int wc, int fr, int fq) const {
;         const int row0 = u.pm * BM + wr * 64 + fr, col0 = u.pn * BM + wc * 32 + 8 * fq;
; #pragma unroll
;         for (int ai = 0; ai < 2; ++ai)
; #pragma unroll
;             for (int m = 0; m < 4; ++m)
; #pragma unroll
;                 for (int bj = 0; bj < 2; ++bj) f(row0 + ai * HALF + m * 16, col0 + bj * HALF, acc[ai][bj][m][0], acc[ai][bj][m][1]);
	v_mov_b32_e32 v30, v238
	v_mov_b32_e32 v31, v239
	v_mov_b32_e32 v32, v240
	v_mov_b32_e32 v33, v241
	v_lshlrev_b32_e32 v38, 16, v33
	v_mul_f32_e32 v28, 0xbfb8aa3b, v22
	v_exp_f32_e32 v28, v28
	v_lshlrev_b32_e32 v26, 16, v30
	v_and_b32_e32 v27, 0xffff0000, v30
	v_lshlrev_b32_e32 v29, 16, v31
	v_add_f32_e32 v28, 1.0, v28
	v_div_scale_f32 v36, s[2:3], v28, v28, v22
	v_rcp_f32_e32 v37, v36
	v_and_b32_e32 v30, 0xffff0000, v31
	v_lshlrev_b32_e32 v31, 16, v32
	v_and_b32_e32 v32, 0xffff0000, v32
	v_fma_f32 v39, -v36, v37, 1.0
	v_fmac_f32_e32 v37, v39, v37
	v_div_scale_f32 v39, vcc, v22, v28, v22
	v_mul_f32_e32 v40, v39, v37
	v_fma_f32 v42, -v36, v40, v39
	v_fmac_f32_e32 v40, v42, v37
	v_fma_f32 v36, -v36, v40, v39
	v_add_f32_e32 v39, 1.0, v41
	v_div_scale_f32 v41, s[2:3], v39, v39, v18
	v_rcp_f32_e32 v42, v41
	v_div_fmas_f32 v36, v36, v37, v40
	v_div_fixup_f32 v22, v36, v28, v22
	v_mul_f32_e32 v36, 0xbfb8aa3b, v23
	v_exp_f32_e32 v36, v36
	v_mul_f32_e32 v22, v22, v26
	v_fma_f32 v26, -v41, v42, 1.0
	v_fmac_f32_e32 v42, v26, v42
	v_div_scale_f32 v26, vcc, v18, v39, v18
	v_mul_f32_e32 v28, v26, v42
	v_fma_f32 v37, -v41, v28, v26
	v_add_f32_e32 v36, 1.0, v36
	v_fmac_f32_e32 v28, v37, v42
	v_div_scale_f32 v37, s[2:3], v36, v36, v23
	v_fma_f32 v26, -v41, v28, v26
	v_rcp_f32_e32 v40, v37
	v_div_fmas_f32 v26, v26, v42, v28
	v_div_fixup_f32 v18, v26, v39, v18
	v_mul_f32_e32 v26, v18, v31
	v_mul_f32_e32 v31, 0xbfb8aa3b, v19
	v_fma_f32 v18, -v37, v40, 1.0
	v_exp_f32_e32 v31, v31
	v_fmac_f32_e32 v40, v18, v40
	v_div_scale_f32 v18, vcc, v23, v36, v23
	v_mul_f32_e32 v28, v18, v40
	v_fma_f32 v39, -v37, v28, v18
	v_fmac_f32_e32 v28, v39, v40
	v_add_f32_e32 v31, 1.0, v31
	v_fma_f32 v18, -v37, v28, v18
	v_div_scale_f32 v37, s[2:3], v31, v31, v19
	v_rcp_f32_e32 v39, v37
	v_div_fmas_f32 v18, v18, v40, v28
	v_mul_f32_e32 v28, 0xbfb8aa3b, v24
	v_exp_f32_e32 v28, v28
	v_div_fixup_f32 v18, v18, v36, v23
	v_fma_f32 v23, -v37, v39, 1.0
	v_fmac_f32_e32 v39, v23, v39
	v_div_scale_f32 v23, vcc, v19, v31, v19
	v_mul_f32_e32 v18, v18, v27
	v_mul_f32_e32 v27, v23, v39
	v_fma_f32 v36, -v37, v27, v23
	v_add_f32_e32 v28, 1.0, v28
	v_fmac_f32_e32 v27, v36, v39
	v_div_scale_f32 v36, s[2:3], v28, v28, v24
	v_fma_f32 v23, -v37, v27, v23
	v_rcp_f32_e32 v37, v36
	v_div_fmas_f32 v23, v23, v39, v27
	v_div_fixup_f32 v19, v23, v31, v19
	v_mul_f32_e32 v31, 0xbfb8aa3b, v20
	v_exp_f32_e32 v31, v31
	v_mul_f32_e32 v23, v19, v32
	v_fma_f32 v19, -v36, v37, 1.0
	v_fmac_f32_e32 v37, v19, v37
	v_div_scale_f32 v19, vcc, v24, v28, v24
	v_mul_f32_e32 v27, v19, v37
	v_fma_f32 v32, -v36, v27, v19
	v_add_f32_e32 v31, 1.0, v31
	v_fmac_f32_e32 v27, v32, v37
	v_div_scale_f32 v32, s[2:3], v31, v31, v20
	v_fma_f32 v19, -v36, v27, v19
	v_rcp_f32_e32 v36, v32
	v_div_fmas_f32 v19, v19, v37, v27
	v_div_fixup_f32 v19, v19, v28, v24
	v_mul_f32_e32 v28, 0xbfb8aa3b, v25
	v_exp_f32_e32 v28, v28
	v_fma_f32 v24, -v32, v36, 1.0
	v_fmac_f32_e32 v36, v24, v36
	v_div_scale_f32 v24, vcc, v20, v31, v20
	v_mul_f32_e32 v27, v24, v36
	v_mul_f32_e32 v19, v19, v29
	v_fma_f32 v29, -v32, v27, v24
	v_add_f32_e32 v28, 1.0, v28
	v_fmac_f32_e32 v27, v29, v36
	v_div_scale_f32 v29, s[2:3], v28, v28, v25
	v_fma_f32 v24, -v32, v27, v24
	v_rcp_f32_e32 v32, v29
	v_div_fmas_f32 v24, v24, v36, v27
	v_div_fixup_f32 v20, v24, v31, v20
	v_mul_f32_e32 v24, v20, v38
	v_fma_f32 v20, -v29, v32, 1.0
	v_mul_f32_e32 v31, 0xbfb8aa3b, v21
	v_fmac_f32_e32 v32, v20, v32
	v_div_scale_f32 v20, vcc, v25, v28, v25
	v_exp_f32_e32 v31, v31
	v_mul_f32_e32 v27, v20, v32
	v_fma_f32 v36, -v29, v27, v20
	v_fmac_f32_e32 v27, v36, v32
	v_fma_f32 v20, -v29, v27, v20
	v_add_f32_e32 v29, 1.0, v31
	v_div_scale_f32 v31, s[2:3], v29, v29, v21
	v_rcp_f32_e32 v36, v31
	v_div_fmas_f32 v20, v20, v32, v27
	v_div_fixup_f32 v20, v20, v28, v25
	v_mul_f32_e32 v20, v20, v30
	v_fma_f32 v25, -v31, v36, 1.0
	v_fmac_f32_e32 v36, v25, v36
	v_div_scale_f32 v25, vcc, v21, v29, v21
	v_mul_f32_e32 v27, v25, v36
	v_fma_f32 v28, -v31, v27, v25
	v_fmac_f32_e32 v27, v28, v36
	v_fma_f32 v25, -v31, v27, v25
	v_div_fmas_f32 v25, v25, v36, v27
	v_and_b32_e32 v33, 0xffff0000, v33
	v_div_fixup_f32 v21, v25, v29, v21
	v_cvt_pk_bf16_f32 v18, v22, v18
	v_cvt_pk_bf16_f32 v19, v19, v20
	v_cvt_pk_bf16_f32 v20, v26, v23
	v_add_co_u32_e32 v26, vcc, s51, v148
	v_mul_f32_e32 v21, v21, v33
	s_nop 0
	v_addc_co_u32_e32 v27, vcc, 0, v149, vcc
	v_cvt_pk_bf16_f32 v21, v24, v21
	s_waitcnt vmcnt(14)
;     __device__ __forceinline__ void operator()(const f32x4 (&acc)[2][2][4][2], const Unit& u, int wr, int wc, int fr, int fq) const {
;         const int row0 = u.pm * BM + wr * 64 + fr, col0 = u.pn * BM + wc * 32 + 8 * fq;
; #pragma unroll
;         for (int ai = 0; ai < 2; ++ai)
; #pragma unroll
;             for (int m = 0; m < 4; ++m)
; #pragma unroll
;                 for (int bj = 0; bj < 2; ++bj) f(row0 + ai * HALF + m * 16, col0 + bj * HALF, acc[ai][bj][m][0], acc[ai][bj][m][1]);
	v_mov_b32_e32 v22, v242
	v_mov_b32_e32 v23, v243
	v_mov_b32_e32 v24, v244
	v_mov_b32_e32 v25, v245
	v_lshlrev_b32_e32 v29, 16, v24
	global_store_dwordx4 v[34:35], v[18:21], off offset:256
	v_mul_f32_e32 v35, 0xbfb8aa3b, v10
	v_exp_f32_e32 v35, v35
	v_lshlrev_b32_e32 v20, 16, v22
	v_and_b32_e32 v21, 0xffff0000, v22
	v_mul_f32_e32 v22, 0xbfb8aa3b, v14
	v_exp_f32_e32 v22, v22
	v_and_b32_e32 v24, 0xffff0000, v24
	v_lshlrev_b32_e32 v28, 16, v23
	v_lshlrev_b32_e32 v32, 16, v25
	v_add_f32_e32 v22, 1.0, v22
	v_div_scale_f32 v30, s[2:3], v22, v22, v14
	v_rcp_f32_e32 v31, v30
	v_and_b32_e32 v23, 0xffff0000, v23
	v_and_b32_e32 v25, 0xffff0000, v25
	v_lshl_add_u64 v[18:19], v[148:149], 0, s[20:21]
	v_fma_f32 v33, -v30, v31, 1.0
	v_fmac_f32_e32 v31, v33, v31
	v_div_scale_f32 v33, vcc, v14, v22, v14
	v_mul_f32_e32 v34, v33, v31
	v_fma_f32 v36, -v30, v34, v33
	v_fmac_f32_e32 v34, v36, v31
	v_fma_f32 v30, -v30, v34, v33
	v_add_f32_e32 v33, 1.0, v35
	v_div_scale_f32 v35, s[2:3], v33, v33, v10
	v_rcp_f32_e32 v36, v35
	v_div_fmas_f32 v30, v30, v31, v34
	v_div_fixup_f32 v14, v30, v22, v14
	v_mul_f32_e32 v30, 0xbfb8aa3b, v15
	v_exp_f32_e32 v30, v30
	v_mul_f32_e32 v14, v14, v20
	v_fma_f32 v20, -v35, v36, 1.0
	v_fmac_f32_e32 v36, v20, v36
	v_div_scale_f32 v20, vcc, v10, v33, v10
	v_mul_f32_e32 v22, v20, v36
	v_fma_f32 v31, -v35, v22, v20
	v_add_f32_e32 v30, 1.0, v30
	v_fmac_f32_e32 v22, v31, v36
	v_div_scale_f32 v31, s[2:3], v30, v30, v15
	v_fma_f32 v20, -v35, v22, v20
	v_rcp_f32_e32 v34, v31
	v_div_fmas_f32 v20, v20, v36, v22
	v_div_fixup_f32 v10, v20, v33, v10
	v_mul_f32_e32 v20, v10, v29
	v_mul_f32_e32 v29, 0xbfb8aa3b, v11
	v_fma_f32 v10, -v31, v34, 1.0
	v_exp_f32_e32 v29, v29
	v_fmac_f32_e32 v34, v10, v34
	v_div_scale_f32 v10, vcc, v15, v30, v15
	v_mul_f32_e32 v22, v10, v34
	v_fma_f32 v33, -v31, v22, v10
	v_fmac_f32_e32 v22, v33, v34
	v_add_f32_e32 v29, 1.0, v29
	v_fma_f32 v10, -v31, v22, v10
	v_div_scale_f32 v31, s[2:3], v29, v29, v11
	v_rcp_f32_e32 v33, v31
	v_div_fmas_f32 v10, v10, v34, v22
	v_mul_f32_e32 v22, 0xbfb8aa3b, v16
	v_div_fixup_f32 v10, v10, v30, v15
	v_fma_f32 v15, -v31, v33, 1.0
	v_exp_f32_e32 v22, v22
	v_fmac_f32_e32 v33, v15, v33
	v_div_scale_f32 v15, vcc, v11, v29, v11
	v_mul_f32_e32 v10, v10, v21
	v_mul_f32_e32 v21, v15, v33
	v_fma_f32 v30, -v31, v21, v15
	v_fmac_f32_e32 v21, v30, v33
	v_add_f32_e32 v22, 1.0, v22
	v_fma_f32 v15, -v31, v21, v15
	v_div_scale_f32 v30, s[2:3], v22, v22, v16
	v_rcp_f32_e32 v31, v30
	v_div_fmas_f32 v15, v15, v33, v21
	v_div_fixup_f32 v11, v15, v29, v11
	v_mul_f32_e32 v15, v11, v24
	v_mul_f32_e32 v24, 0xbfb8aa3b, v12
	v_exp_f32_e32 v24, v24
	v_fma_f32 v11, -v30, v31, 1.0
	v_fmac_f32_e32 v31, v11, v31
	v_div_scale_f32 v11, vcc, v16, v22, v16
	v_mul_f32_e32 v21, v11, v31
	v_fma_f32 v29, -v30, v21, v11
	v_add_f32_e32 v24, 1.0, v24
	v_fmac_f32_e32 v21, v29, v31
	v_div_scale_f32 v29, s[2:3], v24, v24, v12
	v_fma_f32 v11, -v30, v21, v11
	v_rcp_f32_e32 v30, v29
	v_div_fmas_f32 v11, v11, v31, v21
	v_div_fixup_f32 v11, v11, v22, v16
	v_mul_f32_e32 v22, 0xbfb8aa3b, v17
	v_exp_f32_e32 v22, v22
	v_fma_f32 v16, -v29, v30, 1.0
	v_fmac_f32_e32 v30, v16, v30
	v_div_scale_f32 v16, vcc, v12, v24, v12
	v_mul_f32_e32 v21, v16, v30
	v_mul_f32_e32 v11, v11, v28
	v_fma_f32 v28, -v29, v21, v16
	v_add_f32_e32 v22, 1.0, v22
	v_fmac_f32_e32 v21, v28, v30
	v_div_scale_f32 v28, s[2:3], v22, v22, v17
	v_fma_f32 v16, -v29, v21, v16
	v_rcp_f32_e32 v29, v28
	v_div_fmas_f32 v16, v16, v30, v21
	v_div_fixup_f32 v12, v16, v24, v12
	v_mul_f32_e32 v24, 0xbfb8aa3b, v13
	v_mul_f32_e32 v16, v12, v32
	v_fma_f32 v12, -v28, v29, 1.0
	v_exp_f32_e32 v24, v24
	v_fmac_f32_e32 v29, v12, v29
	v_div_scale_f32 v12, vcc, v17, v22, v17
	v_mul_f32_e32 v21, v12, v29
	v_fma_f32 v30, -v28, v21, v12
	v_fmac_f32_e32 v21, v30, v29
	v_add_f32_e32 v24, 1.0, v24
	v_fma_f32 v12, -v28, v21, v12
	v_div_scale_f32 v28, s[2:3], v24, v24, v13
	v_rcp_f32_e32 v30, v28
	v_div_fmas_f32 v12, v12, v29, v21
	v_div_fixup_f32 v12, v12, v22, v17
	v_mul_f32_e32 v12, v12, v23
	v_fma_f32 v17, -v28, v30, 1.0
	v_fmac_f32_e32 v30, v17, v30
	v_div_scale_f32 v17, vcc, v13, v24, v13
	v_mul_f32_e32 v21, v17, v30
	v_fma_f32 v22, -v28, v21, v17
	v_fmac_f32_e32 v21, v22, v30
	v_fma_f32 v17, -v28, v21, v17
	v_div_fmas_f32 v17, v17, v30, v21
	v_div_fixup_f32 v13, v17, v24, v13
	v_mul_f32_e32 v13, v13, v25
	v_cvt_pk_bf16_f32 v10, v14, v10
	v_cvt_pk_bf16_f32 v11, v11, v12
	v_cvt_pk_bf16_f32 v12, v20, v15
	v_cvt_pk_bf16_f32 v13, v16, v13
	v_mul_f32_e32 v25, 0xbfb8aa3b, v2
	global_store_dwordx4 v[26:27], v[10:13], off
	v_exp_f32_e32 v25, v25
	s_waitcnt vmcnt(14)
; #define PG8_WAIT_V(n) asm volatile("s_waitcnt vmcnt(" #n ")" ::: "memory")
; #define PG8_BAR __builtin_amdgcn_s_barrier()
; template <class Epi>
; __device__ __forceinline__ void gemm_phase(PG8_LAS unsigned char* lds, const Gemm g, const StaticOrder& S, const Epi& E) {
;     ...
;         cur = nxt; cA = nA; cB = nB; ++ui;
;     }
;     PG8_WAIT_V(0);
;     if (wr == 0) PG8_BAR;
;     PG8_BAR;
	v_mov_b32_e32 v14, v246
	v_mov_b32_e32 v15, v247
	v_mov_b32_e32 v16, v248
	v_mov_b32_e32 v17, v249
	v_lshlrev_b32_e32 v22, 16, v17
	v_mul_f32_e32 v12, 0xbfb8aa3b, v6
	v_exp_f32_e32 v12, v12
	v_lshlrev_b32_e32 v10, 16, v14
	v_and_b32_e32 v11, 0xffff0000, v14
	v_lshlrev_b32_e32 v13, 16, v15
	v_add_f32_e32 v12, 1.0, v12
	v_div_scale_f32 v20, s[2:3], v12, v12, v6
	v_rcp_f32_e32 v21, v20
	v_and_b32_e32 v14, 0xffff0000, v15
	v_lshlrev_b32_e32 v15, 16, v16
	v_and_b32_e32 v16, 0xffff0000, v16
	v_fma_f32 v23, -v20, v21, 1.0
	v_fmac_f32_e32 v21, v23, v21
	v_div_scale_f32 v23, vcc, v6, v12, v6
	v_mul_f32_e32 v24, v23, v21
	v_fma_f32 v26, -v20, v24, v23
	v_fmac_f32_e32 v24, v26, v21
	v_fma_f32 v20, -v20, v24, v23
	v_add_f32_e32 v23, 1.0, v25
	v_div_scale_f32 v25, s[2:3], v23, v23, v2
	v_rcp_f32_e32 v26, v25
	v_div_fmas_f32 v20, v20, v21, v24
	v_div_fixup_f32 v6, v20, v12, v6
	v_mul_f32_e32 v20, 0xbfb8aa3b, v7
	v_exp_f32_e32 v20, v20
	v_mul_f32_e32 v6, v6, v10
	v_fma_f32 v10, -v25, v26, 1.0
	v_fmac_f32_e32 v26, v10, v26
	v_div_scale_f32 v10, vcc, v2, v23, v2
	v_mul_f32_e32 v12, v10, v26
	v_fma_f32 v21, -v25, v12, v10
	v_add_f32_e32 v20, 1.0, v20
	v_fmac_f32_e32 v12, v21, v26
	v_div_scale_f32 v21, s[2:3], v20, v20, v7
	v_fma_f32 v10, -v25, v12, v10
	v_rcp_f32_e32 v24, v21
	v_div_fmas_f32 v10, v10, v26, v12
	v_div_fixup_f32 v2, v10, v23, v2
	v_mul_f32_e32 v10, v2, v15
	v_mul_f32_e32 v15, 0xbfb8aa3b, v3
	v_fma_f32 v2, -v21, v24, 1.0
	v_exp_f32_e32 v15, v15
	v_fmac_f32_e32 v24, v2, v24
	v_div_scale_f32 v2, vcc, v7, v20, v7
	v_mul_f32_e32 v12, v2, v24
	v_fma_f32 v23, -v21, v12, v2
	v_fmac_f32_e32 v12, v23, v24
	v_add_f32_e32 v15, 1.0, v15
	v_fma_f32 v2, -v21, v12, v2
	v_div_scale_f32 v21, s[2:3], v15, v15, v3
	v_rcp_f32_e32 v23, v21
	v_div_fmas_f32 v2, v2, v24, v12
	v_mul_f32_e32 v12, 0xbfb8aa3b, v8
	v_exp_f32_e32 v12, v12
	v_div_fixup_f32 v2, v2, v20, v7
	v_fma_f32 v7, -v21, v23, 1.0
	v_fmac_f32_e32 v23, v7, v23
	v_div_scale_f32 v7, vcc, v3, v15, v3
	v_mul_f32_e32 v2, v2, v11
	v_mul_f32_e32 v11, v7, v23
	v_fma_f32 v20, -v21, v11, v7
	v_add_f32_e32 v12, 1.0, v12
	v_fmac_f32_e32 v11, v20, v23
	v_div_scale_f32 v20, s[2:3], v12, v12, v8
	v_fma_f32 v7, -v21, v11, v7
	v_rcp_f32_e32 v21, v20
	v_div_fmas_f32 v7, v7, v23, v11
	v_div_fixup_f32 v3, v7, v15, v3
	v_mul_f32_e32 v15, 0xbfb8aa3b, v4
	v_exp_f32_e32 v15, v15
	v_mul_f32_e32 v7, v3, v16
	v_fma_f32 v3, -v20, v21, 1.0
	v_fmac_f32_e32 v21, v3, v21
	v_div_scale_f32 v3, vcc, v8, v12, v8
	v_mul_f32_e32 v11, v3, v21
	v_fma_f32 v16, -v20, v11, v3
	v_add_f32_e32 v15, 1.0, v15
	v_fmac_f32_e32 v11, v16, v21
	v_div_scale_f32 v16, s[2:3], v15, v15, v4
	v_fma_f32 v3, -v20, v11, v3
	v_rcp_f32_e32 v20, v16
	v_div_fmas_f32 v3, v3, v21, v11
	v_div_fixup_f32 v3, v3, v12, v8
	v_mul_f32_e32 v12, 0xbfb8aa3b, v9
	v_exp_f32_e32 v12, v12
	v_fma_f32 v8, -v16, v20, 1.0
	v_fmac_f32_e32 v20, v8, v20
	v_div_scale_f32 v8, vcc, v4, v15, v4
	v_mul_f32_e32 v11, v8, v20
	v_mul_f32_e32 v3, v3, v13
	v_fma_f32 v13, -v16, v11, v8
	v_add_f32_e32 v12, 1.0, v12
	v_fmac_f32_e32 v11, v13, v20
	v_div_scale_f32 v13, s[2:3], v12, v12, v9
	v_fma_f32 v8, -v16, v11, v8
	v_rcp_f32_e32 v16, v13
	v_div_fmas_f32 v8, v8, v20, v11
	v_div_fixup_f32 v4, v8, v15, v4
	v_mul_f32_e32 v8, v4, v22
	v_fma_f32 v4, -v13, v16, 1.0
	v_mul_f32_e32 v15, 0xbfb8aa3b, v5
	v_fmac_f32_e32 v16, v4, v16
	v_div_scale_f32 v4, vcc, v9, v12, v9
	v_exp_f32_e32 v15, v15
	v_mul_f32_e32 v11, v4, v16
	v_fma_f32 v20, -v13, v11, v4
	v_fmac_f32_e32 v11, v20, v16
	v_fma_f32 v4, -v13, v11, v4
	v_add_f32_e32 v13, 1.0, v15
	v_div_scale_f32 v15, s[2:3], v13, v13, v5
	v_rcp_f32_e32 v20, v15
	v_div_fmas_f32 v4, v4, v16, v11
	v_div_fixup_f32 v4, v4, v12, v9
	v_and_b32_e32 v17, 0xffff0000, v17
	v_fma_f32 v9, -v15, v20, 1.0
	v_fmac_f32_e32 v20, v9, v20
	v_div_scale_f32 v9, vcc, v5, v13, v5
	v_mul_f32_e32 v11, v9, v20
	v_fma_f32 v12, -v15, v11, v9
	v_fmac_f32_e32 v11, v12, v20
	v_fma_f32 v9, -v15, v11, v9
	v_div_fmas_f32 v9, v9, v20, v11
	v_div_fixup_f32 v5, v9, v13, v5
	v_mul_f32_e32 v4, v4, v14
	v_mul_f32_e32 v5, v5, v17
	s_and_b64 vcc, exec, s[0:1]
	s_mov_b32 s3, s22
	s_mov_b32 s2, s24
	v_cvt_pk_bf16_f32 v2, v6, v2
	v_cvt_pk_bf16_f32 v3, v3, v4
	v_cvt_pk_bf16_f32 v4, v10, v7
	v_cvt_pk_bf16_f32 v5, v8, v5
	global_store_dwordx4 v[18:19], v[2:5], off offset:256
	s_cbranch_vccz .LBB0_1049
	s_waitcnt vmcnt(0)
	s_cmpk_gt_u32 s33, 0xff
	s_cbranch_scc1 .LBB0_1060
	s_barrier
